# v17: attention K/V tiles staged by LDS-DMA into xor-swizzled rings (K ring 4, V ring 5), no register staging
# speedup vs baseline: 1.0311x; 1.0051x over previous
.LBB0_130:
	s_or_b64 exec, exec, s[0:1]
	s_waitcnt lgkmcnt(0)
	s_barrier
	s_lshl_b32 s100, s2, 2
	s_mov_b32 s101, 0
	v_lshl_add_u64 v[232:233], v[110:111], 0, s[100:101]
	global_load_dwordx4 v[216:219], v[232:233], off
	global_load_dwordx4 v[220:223], v[232:233], off offset:32
	global_load_dwordx4 v[224:227], v[232:233], off offset:64
	global_load_dwordx4 v[228:231], v[232:233], off offset:96
	ds_read_b32 v32, v109 offset:6144
	ds_read_b32 v33, v109 offset:6400
	s_lshl_b32 s0, s2, 1
	s_add_u32 s0, s28, s0
	s_addc_u32 s1, s27, 0
	s_waitcnt lgkmcnt(1)
	v_add_f32_e32 v32, 0, v32
	s_waitcnt lgkmcnt(0)
	v_add_f32_e32 v32, v32, v33
	ds_read_b32 v33, v109 offset:6656
	s_lshl_b32 s2, s2, 2
	s_mov_b32 s3, s4
	v_lshlrev_b32_e32 v35, 16, v136
	v_and_b32_e32 v44, 0xffff0000, v136
	s_waitcnt lgkmcnt(0)
	v_add_f32_e32 v32, v32, v33
	ds_read_b32 v33, v109 offset:6912
	v_mul_f32_e32 v42, 0xbfb8aa3b, v35
	v_exp_f32_e32 v42, v42
	s_waitcnt lgkmcnt(0)
	v_add_f32_e32 v32, v32, v33
	ds_read_b32 v33, v109 offset:7168
	s_waitcnt lgkmcnt(0)
	v_add_f32_e32 v32, v32, v33
	ds_read_b32 v33, v109 offset:7424
	s_waitcnt lgkmcnt(0)
	v_add_f32_e32 v32, v32, v33
	ds_read_b32 v33, v109 offset:7680
	s_waitcnt lgkmcnt(0)
	v_add_f32_e32 v32, v32, v33
	ds_read_b32 v33, v109 offset:7936
	s_waitcnt lgkmcnt(0)
	v_add_f32_e32 v32, v32, v33
	v_fmamk_f32 v32, v32, 0x3b800000, v194
	v_cmp_gt_f32_e32 vcc, s83, v32
	v_mul_f32_e32 v33, 0x4b800000, v32
	s_nop 0
	v_cndmask_b32_e32 v32, v32, v33, vcc
	v_rsq_f32_e32 v32, v32
	s_nop 0
	v_mul_f32_e32 v33, 0x45800000, v32
	v_cndmask_b32_e32 v34, v32, v33, vcc
	v_lshlrev_b64 v[32:33], 11, v[138:139]
	v_lshl_add_u64 v[36:37], s[0:1], 0, v[32:33]
	v_lshl_add_u64 v[32:33], v[110:111], 0, s[2:3]
	v_pk_mul_f32 v[16:17], v[16:17], v[34:35] op_sel_hi:[1,0]
	s_waitcnt vmcnt(0)
	v_mov_b32_e32 v38, v216
	v_mov_b32_e32 v39, v217
	v_mov_b32_e32 v40, v218
	v_mov_b32_e32 v41, v219
	v_pk_mul_f32 v[16:17], v[38:39], v[16:17]
	v_mul_f32_e32 v38, 0xbfb8aa3b, v44
	v_exp_f32_e32 v43, v38
	s_nop 0
	v_pk_add_f32 v[38:39], v[42:43], 1.0 op_sel_hi:[1,0]
	s_nop 0
	v_div_scale_f32 v42, s[2:3], v39, v39, v44
	v_rcp_f32_e32 v43, v42
	s_nop 0
	v_fma_f32 v45, -v42, v43, 1.0
	v_fmac_f32_e32 v43, v45, v43
	v_div_scale_f32 v45, vcc, v44, v39, v44
	v_mul_f32_e32 v46, v45, v43
	v_fma_f32 v47, -v42, v46, v45
	v_fmac_f32_e32 v46, v47, v43
	v_fma_f32 v42, -v42, v46, v45
	v_div_fmas_f32 v42, v42, v43, v46
	v_div_fixup_f32 v39, v42, v39, v44
	v_div_scale_f32 v42, s[2:3], v38, v38, v35
	v_rcp_f32_e32 v43, v42
	s_nop 0
	v_fma_f32 v44, -v42, v43, 1.0
	v_fmac_f32_e32 v43, v44, v43
	v_div_scale_f32 v44, vcc, v35, v38, v35
	v_mul_f32_e32 v45, v44, v43
	v_fma_f32 v46, -v42, v45, v44
	v_fmac_f32_e32 v45, v46, v43
	v_fma_f32 v42, -v42, v45, v44
	v_div_fmas_f32 v42, v42, v43, v45
	v_div_fixup_f32 v38, v42, v38, v35
	v_lshlrev_b32_e32 v35, 16, v137
	v_and_b32_e32 v42, 0xffff0000, v137
	v_pk_mul_f32 v[16:17], v[38:39], v[16:17]
	v_mul_f32_e32 v38, 0xbfb8aa3b, v35
	v_mul_f32_e32 v39, 0xbfb8aa3b, v42
	v_exp_f32_e32 v38, v38
	v_exp_f32_e32 v39, v39
	v_pk_mul_f32 v[18:19], v[18:19], v[34:35] op_sel_hi:[1,0]
	v_pk_add_f32 v[38:39], v[38:39], 1.0 op_sel_hi:[1,0]
	v_pk_mul_f32 v[18:19], v[40:41], v[18:19]
	v_div_scale_f32 v40, s[2:3], v39, v39, v42
	v_rcp_f32_e32 v41, v40
	s_nop 0
	v_fma_f32 v43, -v40, v41, 1.0
	v_fmac_f32_e32 v41, v43, v41
	v_div_scale_f32 v43, vcc, v42, v39, v42
	v_mul_f32_e32 v44, v43, v41
	v_fma_f32 v45, -v40, v44, v43
	v_fmac_f32_e32 v44, v45, v41
	v_fma_f32 v40, -v40, v44, v43
	v_div_fmas_f32 v40, v40, v41, v44
	v_div_fixup_f32 v39, v40, v39, v42
	v_div_scale_f32 v40, s[2:3], v38, v38, v35
	v_rcp_f32_e32 v41, v40
	s_nop 0
	v_fma_f32 v42, -v40, v41, 1.0
	v_fmac_f32_e32 v41, v42, v41
	v_div_scale_f32 v42, vcc, v35, v38, v35
	v_mul_f32_e32 v43, v42, v41
	v_fma_f32 v44, -v40, v43, v42
	v_fmac_f32_e32 v43, v44, v41
	v_fma_f32 v40, -v40, v43, v42
	v_div_fmas_f32 v40, v40, v41, v43
	v_div_fixup_f32 v38, v40, v38, v35
	v_pk_mul_f32 v[18:19], v[38:39], v[18:19]
	v_cvt_pk_bf16_f32 v38, v16, v17
	v_cvt_pk_bf16_f32 v39, v18, v19
	v_lshl_add_u64 v[16:17], v[36:37], 0, v[118:119]
	global_store_dwordx2 v[16:17], v[38:39], off
	v_lshlrev_b32_e32 v35, 16, v134
	v_and_b32_e32 v40, 0xffff0000, v134
	v_mul_f32_e32 v18, 0xbfb8aa3b, v35
	v_mul_f32_e32 v19, 0xbfb8aa3b, v40
	v_exp_f32_e32 v18, v18
	v_exp_f32_e32 v19, v19
	v_pk_mul_f32 v[20:21], v[20:21], v[34:35] op_sel_hi:[1,0]
	v_pk_add_f32 v[18:19], v[18:19], 1.0 op_sel_hi:[1,0]
	v_mov_b32_e32 v36, v220
	v_mov_b32_e32 v37, v221
	v_mov_b32_e32 v38, v222
	v_mov_b32_e32 v39, v223
	v_pk_mul_f32 v[20:21], v[36:37], v[20:21]
	v_div_scale_f32 v36, s[2:3], v19, v19, v40
	v_rcp_f32_e32 v37, v36
	s_nop 0
	v_fma_f32 v41, -v36, v37, 1.0
	v_fmac_f32_e32 v37, v41, v37
	v_div_scale_f32 v41, vcc, v40, v19, v40
	v_mul_f32_e32 v42, v41, v37
	v_fma_f32 v43, -v36, v42, v41
	v_fmac_f32_e32 v42, v43, v37
	v_fma_f32 v36, -v36, v42, v41
	v_div_fmas_f32 v36, v36, v37, v42
	v_div_fixup_f32 v19, v36, v19, v40
	v_div_scale_f32 v36, s[2:3], v18, v18, v35
	v_rcp_f32_e32 v37, v36
	s_nop 0
	v_fma_f32 v40, -v36, v37, 1.0
	v_fmac_f32_e32 v37, v40, v37
	v_div_scale_f32 v40, vcc, v35, v18, v35
	v_mul_f32_e32 v41, v40, v37
	v_fma_f32 v42, -v36, v41, v40
	v_fmac_f32_e32 v41, v42, v37
	v_fma_f32 v36, -v36, v41, v40
	v_div_fmas_f32 v36, v36, v37, v41
	v_div_fixup_f32 v18, v36, v18, v35
	v_lshlrev_b32_e32 v35, 16, v135
	v_and_b32_e32 v36, 0xffff0000, v135
	v_pk_mul_f32 v[18:19], v[18:19], v[20:21]
	v_mul_f32_e32 v20, 0xbfb8aa3b, v35
	v_mul_f32_e32 v21, 0xbfb8aa3b, v36
	v_exp_f32_e32 v20, v20
	v_exp_f32_e32 v21, v21
	v_pk_mul_f32 v[22:23], v[22:23], v[34:35] op_sel_hi:[1,0]
	v_cvt_pk_bf16_f32 v18, v18, v19
	v_pk_mul_f32 v[22:23], v[38:39], v[22:23]
	v_pk_add_f32 v[20:21], v[20:21], 1.0 op_sel_hi:[1,0]
	s_nop 0
	v_div_scale_f32 v37, s[2:3], v21, v21, v36
	v_rcp_f32_e32 v38, v37
	s_nop 0
	v_fma_f32 v39, -v37, v38, 1.0
	v_fmac_f32_e32 v38, v39, v38
	v_div_scale_f32 v39, vcc, v36, v21, v36
	v_mul_f32_e32 v40, v39, v38
	v_fma_f32 v41, -v37, v40, v39
	v_fmac_f32_e32 v40, v41, v38
	v_fma_f32 v37, -v37, v40, v39
	v_div_fmas_f32 v37, v37, v38, v40
	v_div_fixup_f32 v21, v37, v21, v36
	v_div_scale_f32 v36, s[2:3], v20, v20, v35
	v_rcp_f32_e32 v37, v36
	s_nop 0
	v_fma_f32 v38, -v36, v37, 1.0
	v_fmac_f32_e32 v37, v38, v37
	v_div_scale_f32 v38, vcc, v35, v20, v35
	v_mul_f32_e32 v39, v38, v37
	v_fma_f32 v40, -v36, v39, v38
	v_fmac_f32_e32 v39, v40, v37
	v_fma_f32 v36, -v36, v39, v38
	v_div_fmas_f32 v36, v36, v37, v39
	v_div_fixup_f32 v20, v36, v20, v35
	v_pk_mul_f32 v[20:21], v[20:21], v[22:23]
	v_lshlrev_b32_e32 v35, 16, v132
	v_cvt_pk_bf16_f32 v19, v20, v21
	global_store_dwordx2 v[16:17], v[18:19], off offset:16
	v_and_b32_e32 v36, 0xffff0000, v132
	v_mul_f32_e32 v22, 0xbfb8aa3b, v35
	v_mul_f32_e32 v23, 0xbfb8aa3b, v36
	v_exp_f32_e32 v22, v22
	v_exp_f32_e32 v23, v23
	v_pk_mul_f32 v[24:25], v[24:25], v[34:35] op_sel_hi:[1,0]
	v_pk_add_f32 v[22:23], v[22:23], 1.0 op_sel_hi:[1,0]
	v_mov_b32_e32 v18, v224
	v_mov_b32_e32 v19, v225
	v_mov_b32_e32 v20, v226
	v_mov_b32_e32 v21, v227
	v_pk_mul_f32 v[18:19], v[18:19], v[24:25]
	v_div_scale_f32 v24, s[2:3], v23, v23, v36
	v_rcp_f32_e32 v25, v24
	s_nop 0
	v_fma_f32 v37, -v24, v25, 1.0
	v_fmac_f32_e32 v25, v37, v25
	v_div_scale_f32 v37, vcc, v36, v23, v36
	v_mul_f32_e32 v38, v37, v25
	v_fma_f32 v39, -v24, v38, v37
	v_fmac_f32_e32 v38, v39, v25
	v_fma_f32 v24, -v24, v38, v37
	v_div_fmas_f32 v24, v24, v25, v38
	v_div_fixup_f32 v23, v24, v23, v36
	v_div_scale_f32 v24, s[2:3], v22, v22, v35
	v_rcp_f32_e32 v25, v24
	s_nop 0
	v_fma_f32 v36, -v24, v25, 1.0
	v_fmac_f32_e32 v25, v36, v25
	v_div_scale_f32 v36, vcc, v35, v22, v35
	v_mul_f32_e32 v37, v36, v25
	v_fma_f32 v38, -v24, v37, v36
	v_fmac_f32_e32 v37, v38, v25
	v_fma_f32 v24, -v24, v37, v36
	v_div_fmas_f32 v24, v24, v25, v37
	v_div_fixup_f32 v22, v24, v22, v35
	v_lshlrev_b32_e32 v35, 16, v133
	v_and_b32_e32 v36, 0xffff0000, v133
	v_pk_mul_f32 v[18:19], v[22:23], v[18:19]
	v_mul_f32_e32 v22, 0xbfb8aa3b, v35
	v_mul_f32_e32 v23, 0xbfb8aa3b, v36
	v_exp_f32_e32 v22, v22
	v_exp_f32_e32 v23, v23
	v_pk_mul_f32 v[24:25], v[26:27], v[34:35] op_sel_hi:[1,0]
	v_cvt_pk_bf16_f32 v18, v18, v19
	v_pk_mul_f32 v[20:21], v[20:21], v[24:25]
	v_pk_add_f32 v[22:23], v[22:23], 1.0 op_sel_hi:[1,0]
	s_nop 0
	v_div_scale_f32 v24, s[2:3], v23, v23, v36
	v_rcp_f32_e32 v25, v24
	s_nop 0
	v_fma_f32 v26, -v24, v25, 1.0
	v_fmac_f32_e32 v25, v26, v25
	v_div_scale_f32 v26, vcc, v36, v23, v36
	v_mul_f32_e32 v27, v26, v25
	v_fma_f32 v37, -v24, v27, v26
	v_fmac_f32_e32 v27, v37, v25
	v_fma_f32 v24, -v24, v27, v26
	v_div_fmas_f32 v24, v24, v25, v27
	v_div_fixup_f32 v23, v24, v23, v36
	v_div_scale_f32 v24, s[2:3], v22, v22, v35
	v_rcp_f32_e32 v25, v24
	s_nop 0
	v_fma_f32 v26, -v24, v25, 1.0
	v_fmac_f32_e32 v25, v26, v25
	v_div_scale_f32 v26, vcc, v35, v22, v35
	v_mul_f32_e32 v27, v26, v25
	v_fma_f32 v36, -v24, v27, v26
	v_fmac_f32_e32 v27, v36, v25
	v_fma_f32 v24, -v24, v27, v26
	v_div_fmas_f32 v24, v24, v25, v27
	v_div_fixup_f32 v22, v24, v22, v35
	v_pk_mul_f32 v[20:21], v[22:23], v[20:21]
	v_lshlrev_b32_e32 v26, 16, v130
	v_cvt_pk_bf16_f32 v19, v20, v21
	global_store_dwordx2 v[16:17], v[18:19], off offset:32
	v_and_b32_e32 v27, 0xffff0000, v130
	v_mul_f32_e32 v22, 0xbfb8aa3b, v26
	v_mul_f32_e32 v23, 0xbfb8aa3b, v27
	v_exp_f32_e32 v22, v22
	v_exp_f32_e32 v23, v23
	v_pk_mul_f32 v[24:25], v[28:29], v[34:35] op_sel_hi:[1,0]
	v_pk_add_f32 v[22:23], v[22:23], 1.0 op_sel_hi:[1,0]
	v_mov_b32_e32 v18, v228
	v_mov_b32_e32 v19, v229
	v_mov_b32_e32 v20, v230
	v_mov_b32_e32 v21, v231
	v_pk_mul_f32 v[18:19], v[18:19], v[24:25]
	v_div_scale_f32 v24, s[2:3], v23, v23, v27
	v_rcp_f32_e32 v25, v24
	s_nop 0
	v_fma_f32 v28, -v24, v25, 1.0
	v_fmac_f32_e32 v25, v28, v25
	v_div_scale_f32 v28, vcc, v27, v23, v27
	v_mul_f32_e32 v29, v28, v25
	v_fma_f32 v35, -v24, v29, v28
	v_fmac_f32_e32 v29, v35, v25
	v_fma_f32 v24, -v24, v29, v28
	v_div_fmas_f32 v24, v24, v25, v29
	v_div_fixup_f32 v23, v24, v23, v27
	v_div_scale_f32 v24, s[2:3], v22, v22, v26
	v_rcp_f32_e32 v25, v24
	s_nop 0
	v_fma_f32 v27, -v24, v25, 1.0
	v_fmac_f32_e32 v25, v27, v25
	v_div_scale_f32 v27, vcc, v26, v22, v26
	v_mul_f32_e32 v28, v27, v25
	v_fma_f32 v29, -v24, v28, v27
	v_fmac_f32_e32 v28, v29, v25
	v_fma_f32 v24, -v24, v28, v27
	v_div_fmas_f32 v24, v24, v25, v28
	v_div_fixup_f32 v22, v24, v22, v26
	v_lshlrev_b32_e32 v26, 16, v131
	v_and_b32_e32 v27, 0xffff0000, v131
	v_pk_mul_f32 v[18:19], v[22:23], v[18:19]
	v_mul_f32_e32 v22, 0xbfb8aa3b, v26
	v_mul_f32_e32 v23, 0xbfb8aa3b, v27
	v_exp_f32_e32 v22, v22
	v_exp_f32_e32 v23, v23
	v_pk_mul_f32 v[24:25], v[30:31], v[34:35] op_sel_hi:[1,0]
	v_cvt_pk_bf16_f32 v18, v18, v19
	v_pk_mul_f32 v[20:21], v[20:21], v[24:25]
	v_pk_add_f32 v[22:23], v[22:23], 1.0 op_sel_hi:[1,0]
	s_nop 0
	v_div_scale_f32 v24, s[2:3], v23, v23, v27
	v_rcp_f32_e32 v25, v24
	s_nop 0
	v_fma_f32 v28, -v24, v25, 1.0
	v_fmac_f32_e32 v25, v28, v25
	v_div_scale_f32 v28, vcc, v27, v23, v27
	v_mul_f32_e32 v29, v28, v25
	v_fma_f32 v30, -v24, v29, v28
	v_fmac_f32_e32 v29, v30, v25
	v_fma_f32 v24, -v24, v29, v28
	v_div_fmas_f32 v24, v24, v25, v29
	v_div_fixup_f32 v23, v24, v23, v27
	v_div_scale_f32 v24, s[2:3], v22, v22, v26
	v_rcp_f32_e32 v25, v24
	s_nop 0
	v_fma_f32 v27, -v24, v25, 1.0
	v_fmac_f32_e32 v25, v27, v25
	v_div_scale_f32 v27, vcc, v26, v22, v26
	v_mul_f32_e32 v28, v27, v25
	v_fma_f32 v29, -v24, v28, v27
	v_fmac_f32_e32 v28, v29, v25
	v_fma_f32 v24, -v24, v28, v27
	v_div_fmas_f32 v24, v24, v25, v28
	v_div_fixup_f32 v22, v24, v22, v26
	v_pk_mul_f32 v[20:21], v[22:23], v[20:21]
	v_and_b32_e32 v26, 0xffff0000, v126
	v_cvt_pk_bf16_f32 v19, v20, v21
	global_store_dwordx2 v[16:17], v[18:19], off offset:48
	ds_read_b32 v16, v109 offset:6272
	ds_read_b32 v17, v109 offset:6528
	v_lshlrev_b64 v[18:19], 11, v[128:129]
	v_lshl_add_u64 v[18:19], s[0:1], 0, v[18:19]
	s_waitcnt lgkmcnt(0)
	v_add_f32_e32 v16, 0, v16
	v_add_f32_e32 v16, v16, v17
	ds_read_b32 v17, v109 offset:6784
	s_waitcnt lgkmcnt(0)
	v_add_f32_e32 v16, v16, v17
	ds_read_b32 v17, v109 offset:7040
	s_waitcnt lgkmcnt(0)
	v_add_f32_e32 v16, v16, v17
	ds_read_b32 v17, v109 offset:7296
	s_waitcnt lgkmcnt(0)
	v_add_f32_e32 v16, v16, v17
	ds_read_b32 v17, v109 offset:7552
	s_waitcnt lgkmcnt(0)
	v_add_f32_e32 v16, v16, v17
	ds_read_b32 v17, v109 offset:7808
	s_waitcnt lgkmcnt(0)
	v_add_f32_e32 v16, v16, v17
	ds_read_b32 v17, v109 offset:8064
	s_waitcnt lgkmcnt(0)
	v_add_f32_e32 v16, v16, v17
	v_fmamk_f32 v16, v16, 0x3b800000, v194
	v_cmp_gt_f32_e32 vcc, s83, v16
	v_mul_f32_e32 v17, 0x4b800000, v16
	s_nop 0
	v_cndmask_b32_e32 v16, v16, v17, vcc
	v_rsq_f32_e32 v16, v16
	s_nop 0
	v_mul_f32_e32 v17, 0x45800000, v16
	v_cndmask_b32_e32 v16, v16, v17, vcc
	v_lshlrev_b32_e32 v17, 16, v126
	v_pk_mul_f32 v[0:1], v[0:1], v[16:17] op_sel_hi:[1,0]
	v_mul_f32_e32 v24, 0xbfb8aa3b, v17
	v_exp_f32_e32 v24, v24
	v_mov_b32_e32 v20, v216
	v_mov_b32_e32 v21, v217
	v_mov_b32_e32 v22, v218
	v_mov_b32_e32 v23, v219
	v_pk_mul_f32 v[0:1], v[20:21], v[0:1]
	v_mul_f32_e32 v20, 0xbfb8aa3b, v26
	v_exp_f32_e32 v25, v20
	s_nop 0
	v_pk_add_f32 v[20:21], v[24:25], 1.0 op_sel_hi:[1,0]
	s_nop 0
	v_div_scale_f32 v24, s[0:1], v21, v21, v26
	v_rcp_f32_e32 v25, v24
	s_nop 0
	v_fma_f32 v27, -v24, v25, 1.0
	v_fmac_f32_e32 v25, v27, v25
	v_div_scale_f32 v27, vcc, v26, v21, v26
	v_mul_f32_e32 v28, v27, v25
	v_fma_f32 v29, -v24, v28, v27
	v_fmac_f32_e32 v28, v29, v25
	v_fma_f32 v24, -v24, v28, v27
	v_div_fmas_f32 v24, v24, v25, v28
	v_div_fixup_f32 v21, v24, v21, v26
	v_div_scale_f32 v24, s[0:1], v20, v20, v17
	v_rcp_f32_e32 v25, v24
	s_nop 0
	v_fma_f32 v26, -v24, v25, 1.0
	v_fmac_f32_e32 v25, v26, v25
	v_div_scale_f32 v26, vcc, v17, v20, v17
	v_mul_f32_e32 v27, v26, v25
	v_fma_f32 v28, -v24, v27, v26
	v_fmac_f32_e32 v27, v28, v25
	v_fma_f32 v24, -v24, v27, v26
	v_div_fmas_f32 v24, v24, v25, v27
	v_div_fixup_f32 v20, v24, v20, v17
	v_lshlrev_b32_e32 v17, 16, v127
	v_and_b32_e32 v24, 0xffff0000, v127
	v_pk_mul_f32 v[0:1], v[20:21], v[0:1]
	v_mul_f32_e32 v20, 0xbfb8aa3b, v17
	v_mul_f32_e32 v21, 0xbfb8aa3b, v24
	v_exp_f32_e32 v20, v20
	v_exp_f32_e32 v21, v21
	v_pk_mul_f32 v[2:3], v[2:3], v[16:17] op_sel_hi:[1,0]
	v_pk_add_f32 v[20:21], v[20:21], 1.0 op_sel_hi:[1,0]
	v_pk_mul_f32 v[2:3], v[22:23], v[2:3]
	v_div_scale_f32 v22, s[0:1], v21, v21, v24
	v_rcp_f32_e32 v23, v22
	s_nop 0
	v_fma_f32 v25, -v22, v23, 1.0
	v_fmac_f32_e32 v23, v25, v23
	v_div_scale_f32 v25, vcc, v24, v21, v24
	v_mul_f32_e32 v26, v25, v23
	v_fma_f32 v27, -v22, v26, v25
	v_fmac_f32_e32 v26, v27, v23
	v_fma_f32 v22, -v22, v26, v25
	v_div_fmas_f32 v22, v22, v23, v26
	v_div_fixup_f32 v21, v22, v21, v24
	v_div_scale_f32 v22, s[0:1], v20, v20, v17
	v_rcp_f32_e32 v23, v22
	s_nop 0
	v_fma_f32 v24, -v22, v23, 1.0
	v_fmac_f32_e32 v23, v24, v23
	v_div_scale_f32 v24, vcc, v17, v20, v17
	v_mul_f32_e32 v25, v24, v23
	v_fma_f32 v26, -v22, v25, v24
	v_fmac_f32_e32 v25, v26, v23
	v_fma_f32 v22, -v22, v25, v24
	v_div_fmas_f32 v22, v22, v23, v25
	v_div_fixup_f32 v20, v22, v20, v17
	v_pk_mul_f32 v[2:3], v[20:21], v[2:3]
	v_cvt_pk_bf16_f32 v20, v0, v1
	v_cvt_pk_bf16_f32 v21, v2, v3
	v_lshl_add_u64 v[0:1], v[18:19], 0, v[118:119]
	global_store_dwordx2 v[0:1], v[20:21], off
	v_lshlrev_b32_e32 v17, 16, v124
	v_and_b32_e32 v22, 0xffff0000, v124
	v_mul_f32_e32 v2, 0xbfb8aa3b, v17
	v_mul_f32_e32 v3, 0xbfb8aa3b, v22
	v_exp_f32_e32 v2, v2
	v_exp_f32_e32 v3, v3
	v_pk_mul_f32 v[4:5], v[4:5], v[16:17] op_sel_hi:[1,0]
	v_pk_add_f32 v[2:3], v[2:3], 1.0 op_sel_hi:[1,0]
	v_mov_b32_e32 v18, v220
	v_mov_b32_e32 v19, v221
	v_mov_b32_e32 v20, v222
	v_mov_b32_e32 v21, v223
	v_pk_mul_f32 v[4:5], v[18:19], v[4:5]
	v_div_scale_f32 v18, s[0:1], v3, v3, v22
	v_rcp_f32_e32 v19, v18
	s_nop 0
	v_fma_f32 v23, -v18, v19, 1.0
	v_fmac_f32_e32 v19, v23, v19
	v_div_scale_f32 v23, vcc, v22, v3, v22
	v_mul_f32_e32 v24, v23, v19
	v_fma_f32 v25, -v18, v24, v23
	v_fmac_f32_e32 v24, v25, v19
	v_fma_f32 v18, -v18, v24, v23
	v_div_fmas_f32 v18, v18, v19, v24
	v_div_fixup_f32 v3, v18, v3, v22
	v_div_scale_f32 v18, s[0:1], v2, v2, v17
	v_rcp_f32_e32 v19, v18
	s_nop 0
	v_fma_f32 v22, -v18, v19, 1.0
	v_fmac_f32_e32 v19, v22, v19
	v_div_scale_f32 v22, vcc, v17, v2, v17
	v_mul_f32_e32 v23, v22, v19
	v_fma_f32 v24, -v18, v23, v22
	v_fmac_f32_e32 v23, v24, v19
	v_fma_f32 v18, -v18, v23, v22
	v_div_fmas_f32 v18, v18, v19, v23
	v_div_fixup_f32 v2, v18, v2, v17
	v_lshlrev_b32_e32 v17, 16, v125
	v_and_b32_e32 v18, 0xffff0000, v125
	v_pk_mul_f32 v[2:3], v[2:3], v[4:5]
	v_mul_f32_e32 v4, 0xbfb8aa3b, v17
	v_mul_f32_e32 v5, 0xbfb8aa3b, v18
	v_exp_f32_e32 v4, v4
	v_exp_f32_e32 v5, v5
	v_pk_mul_f32 v[6:7], v[6:7], v[16:17] op_sel_hi:[1,0]
	v_cvt_pk_bf16_f32 v2, v2, v3
	v_pk_mul_f32 v[6:7], v[20:21], v[6:7]
	v_pk_add_f32 v[4:5], v[4:5], 1.0 op_sel_hi:[1,0]
	s_nop 0
	v_div_scale_f32 v19, s[0:1], v5, v5, v18
	v_rcp_f32_e32 v20, v19
	s_nop 0
	v_fma_f32 v21, -v19, v20, 1.0
	v_fmac_f32_e32 v20, v21, v20
	v_div_scale_f32 v21, vcc, v18, v5, v18
	v_mul_f32_e32 v22, v21, v20
	v_fma_f32 v23, -v19, v22, v21
	v_fmac_f32_e32 v22, v23, v20
	v_fma_f32 v19, -v19, v22, v21
	v_div_fmas_f32 v19, v19, v20, v22
	v_div_fixup_f32 v5, v19, v5, v18
	v_div_scale_f32 v18, s[0:1], v4, v4, v17
	v_rcp_f32_e32 v19, v18
	s_nop 0
	v_fma_f32 v20, -v18, v19, 1.0
	v_fmac_f32_e32 v19, v20, v19
	v_div_scale_f32 v20, vcc, v17, v4, v17
	v_mul_f32_e32 v21, v20, v19
	v_fma_f32 v22, -v18, v21, v20
	v_fmac_f32_e32 v21, v22, v19
	v_fma_f32 v18, -v18, v21, v20
	v_div_fmas_f32 v18, v18, v19, v21
	v_div_fixup_f32 v4, v18, v4, v17
	v_pk_mul_f32 v[4:5], v[4:5], v[6:7]
	v_lshlrev_b32_e32 v17, 16, v122
	v_cvt_pk_bf16_f32 v3, v4, v5
	global_store_dwordx2 v[0:1], v[2:3], off offset:16
	v_and_b32_e32 v18, 0xffff0000, v122
	v_mul_f32_e32 v6, 0xbfb8aa3b, v17
	v_mul_f32_e32 v7, 0xbfb8aa3b, v18
	v_exp_f32_e32 v6, v6
	v_exp_f32_e32 v7, v7
	v_pk_mul_f32 v[8:9], v[8:9], v[16:17] op_sel_hi:[1,0]
	v_pk_add_f32 v[6:7], v[6:7], 1.0 op_sel_hi:[1,0]
	v_mov_b32_e32 v2, v224
	v_mov_b32_e32 v3, v225
	v_mov_b32_e32 v4, v226
	v_mov_b32_e32 v5, v227
	v_pk_mul_f32 v[2:3], v[2:3], v[8:9]
	v_div_scale_f32 v8, s[0:1], v7, v7, v18
	v_rcp_f32_e32 v9, v8
	s_nop 0
	v_fma_f32 v19, -v8, v9, 1.0
	v_fmac_f32_e32 v9, v19, v9
	v_div_scale_f32 v19, vcc, v18, v7, v18
	v_mul_f32_e32 v20, v19, v9
	v_fma_f32 v21, -v8, v20, v19
	v_fmac_f32_e32 v20, v21, v9
	v_fma_f32 v8, -v8, v20, v19
	v_div_fmas_f32 v8, v8, v9, v20
	v_div_fixup_f32 v7, v8, v7, v18
	v_div_scale_f32 v8, s[0:1], v6, v6, v17
	v_rcp_f32_e32 v9, v8
	s_nop 0
	v_fma_f32 v18, -v8, v9, 1.0
	v_fmac_f32_e32 v9, v18, v9
	v_div_scale_f32 v18, vcc, v17, v6, v17
	v_mul_f32_e32 v19, v18, v9
	v_fma_f32 v20, -v8, v19, v18
	v_fmac_f32_e32 v19, v20, v9
	v_fma_f32 v8, -v8, v19, v18
	v_div_fmas_f32 v8, v8, v9, v19
	v_div_fixup_f32 v6, v8, v6, v17
	v_lshlrev_b32_e32 v17, 16, v123
	v_and_b32_e32 v18, 0xffff0000, v123
	v_pk_mul_f32 v[2:3], v[6:7], v[2:3]
	v_mul_f32_e32 v6, 0xbfb8aa3b, v17
	v_mul_f32_e32 v7, 0xbfb8aa3b, v18
	v_exp_f32_e32 v6, v6
	v_exp_f32_e32 v7, v7
	v_pk_mul_f32 v[8:9], v[10:11], v[16:17] op_sel_hi:[1,0]
	v_cvt_pk_bf16_f32 v2, v2, v3
	v_pk_mul_f32 v[4:5], v[4:5], v[8:9]
	v_pk_add_f32 v[6:7], v[6:7], 1.0 op_sel_hi:[1,0]
	s_nop 0
	v_div_scale_f32 v8, s[0:1], v7, v7, v18
	v_rcp_f32_e32 v9, v8
	s_nop 0
	v_fma_f32 v10, -v8, v9, 1.0
	v_fmac_f32_e32 v9, v10, v9
	v_div_scale_f32 v10, vcc, v18, v7, v18
	v_mul_f32_e32 v11, v10, v9
	v_fma_f32 v19, -v8, v11, v10
	v_fmac_f32_e32 v11, v19, v9
	v_fma_f32 v8, -v8, v11, v10
	v_div_fmas_f32 v8, v8, v9, v11
	v_div_fixup_f32 v7, v8, v7, v18
	v_div_scale_f32 v8, s[0:1], v6, v6, v17
	v_rcp_f32_e32 v9, v8
	s_nop 0
	v_fma_f32 v10, -v8, v9, 1.0
	v_fmac_f32_e32 v9, v10, v9
	v_div_scale_f32 v10, vcc, v17, v6, v17
	v_mul_f32_e32 v11, v10, v9
	v_fma_f32 v18, -v8, v11, v10
	v_fmac_f32_e32 v11, v18, v9
	v_fma_f32 v8, -v8, v11, v10
	v_div_fmas_f32 v8, v8, v9, v11
	v_div_fixup_f32 v6, v8, v6, v17
	v_pk_mul_f32 v[4:5], v[6:7], v[4:5]
	v_lshlrev_b32_e32 v10, 16, v120
	v_cvt_pk_bf16_f32 v3, v4, v5
	global_store_dwordx2 v[0:1], v[2:3], off offset:32
	v_and_b32_e32 v11, 0xffff0000, v120
	v_mul_f32_e32 v6, 0xbfb8aa3b, v10
	v_mul_f32_e32 v7, 0xbfb8aa3b, v11
	v_exp_f32_e32 v6, v6
	v_exp_f32_e32 v7, v7
	v_pk_mul_f32 v[8:9], v[12:13], v[16:17] op_sel_hi:[1,0]
	v_pk_add_f32 v[6:7], v[6:7], 1.0 op_sel_hi:[1,0]
	v_mov_b32_e32 v2, v228
	v_mov_b32_e32 v3, v229
	v_mov_b32_e32 v4, v230
	v_mov_b32_e32 v5, v231
	v_pk_mul_f32 v[2:3], v[2:3], v[8:9]
	v_div_scale_f32 v8, s[0:1], v7, v7, v11
	v_rcp_f32_e32 v9, v8
	s_nop 0
	v_fma_f32 v12, -v8, v9, 1.0
	v_fmac_f32_e32 v9, v12, v9
	v_div_scale_f32 v12, vcc, v11, v7, v11
	v_mul_f32_e32 v13, v12, v9
	v_fma_f32 v17, -v8, v13, v12
	v_fmac_f32_e32 v13, v17, v9
	v_fma_f32 v8, -v8, v13, v12
	v_div_fmas_f32 v8, v8, v9, v13
	v_div_fixup_f32 v7, v8, v7, v11
	v_div_scale_f32 v8, s[0:1], v6, v6, v10
	v_rcp_f32_e32 v9, v8
	s_nop 0
	v_fma_f32 v11, -v8, v9, 1.0
	v_fmac_f32_e32 v9, v11, v9
	v_div_scale_f32 v11, vcc, v10, v6, v10
	v_mul_f32_e32 v12, v11, v9
	v_fma_f32 v13, -v8, v12, v11
	v_fmac_f32_e32 v12, v13, v9
	v_fma_f32 v8, -v8, v12, v11
	v_div_fmas_f32 v8, v8, v9, v12
	v_div_fixup_f32 v6, v8, v6, v10
	v_lshlrev_b32_e32 v10, 16, v121
	v_and_b32_e32 v11, 0xffff0000, v121
	v_pk_mul_f32 v[2:3], v[6:7], v[2:3]
	v_mul_f32_e32 v6, 0xbfb8aa3b, v10
	v_mul_f32_e32 v7, 0xbfb8aa3b, v11
	v_exp_f32_e32 v6, v6
	v_exp_f32_e32 v7, v7
	v_pk_mul_f32 v[8:9], v[14:15], v[16:17] op_sel_hi:[1,0]
	v_cvt_pk_bf16_f32 v2, v2, v3
	v_pk_mul_f32 v[4:5], v[4:5], v[8:9]
	v_pk_add_f32 v[6:7], v[6:7], 1.0 op_sel_hi:[1,0]
	s_nop 0
	v_div_scale_f32 v8, s[0:1], v7, v7, v11
	v_rcp_f32_e32 v9, v8
	s_nop 0
	v_fma_f32 v12, -v8, v9, 1.0
	v_fmac_f32_e32 v9, v12, v9
	v_div_scale_f32 v12, vcc, v11, v7, v11
	v_mul_f32_e32 v13, v12, v9
	v_fma_f32 v14, -v8, v13, v12
	v_fmac_f32_e32 v13, v14, v9
	v_fma_f32 v8, -v8, v13, v12
	v_div_fmas_f32 v8, v8, v9, v13
	v_div_fixup_f32 v7, v8, v7, v11
	v_div_scale_f32 v8, s[0:1], v6, v6, v10
	v_rcp_f32_e32 v9, v8
	v_readlane_b32 s0, v247, 1
	s_add_i32 s10, s10, s0
	v_readlane_b32 s0, v245, 6
	v_fma_f32 v11, -v8, v9, 1.0
	v_fmac_f32_e32 v9, v11, v9
	v_div_scale_f32 v11, vcc, v10, v6, v10
	v_mul_f32_e32 v12, v11, v9
	v_fma_f32 v13, -v8, v12, v11
	v_fmac_f32_e32 v12, v13, v9
	v_fma_f32 v8, -v8, v12, v11
	v_div_fmas_f32 v8, v8, v9, v12
	v_div_fixup_f32 v6, v8, v6, v10
	v_pk_mul_f32 v[4:5], v[6:7], v[4:5]
	s_add_i32 s66, s66, s0
	v_cvt_pk_bf16_f32 v3, v4, v5
	s_cmpk_gt_i32 s10, 0x7ff
	global_store_dwordx2 v[0:1], v[2:3], off offset:48
	s_waitcnt lgkmcnt(0)
	s_barrier
	v_readlane_b32 s1, v247, 2
	s_cbranch_scc1 .LBB0_136

.LBB0_234:
	s_lshr_b32 s6, s27, 18
	s_add_i32 s6, s6, 3
	v_readfirstlane_b32 s8, v195
	s_lshr_b32 s8, s8, 6
	s_lshl_b32 s68, s8, 10
	s_lshl_b32 s69, s8, 11
	s_add_i32 s69, s69, 0
	v_and_b32_e32 v181, 63, v195
	v_lshrrev_b32_e32 v182, 3, v181
	v_lshl_add_u32 v182, s8, 3, v182
	v_bfe_u32 v183, v182, 1, 3
	v_and_b32_e32 v180, 7, v181
	v_xor_b32_e32 v180, v180, v183
	v_lshlrev_b32_e32 v180, 4, v180
	v_lshl_add_u32 v154, v182, 12, v180
	v_lshrrev_b32_e32 v182, 4, v181
	v_lshlrev_b32_e32 v183, 2, v182
	v_and_b32_e32 v180, 15, v181
	v_xor_b32_e32 v180, v180, v183
	v_lshlrev_b32_e32 v180, 4, v180
	v_lshl_add_u32 v182, s8, 3, v182
	v_lshl_add_u32 v155, v182, 12, v180
	v_add_u32_e32 v156, 0x4000, v155
	v_and_b32_e32 v182, 31, v181
	v_lshrrev_b32_e32 v183, 5, v181
	v_bfe_u32 v180, v182, 1, 3
	v_or_b32_e32 v157, 0, v183
	v_xor_b32_e32 v157, v157, v180
	v_lshlrev_b32_e32 v157, 4, v157
	v_lshl_add_u32 v157, v182, 7, v157
	v_or_b32_e32 v158, 2, v183
	v_xor_b32_e32 v158, v158, v180
	v_lshlrev_b32_e32 v158, 4, v158
	v_lshl_add_u32 v158, v182, 7, v158
	v_or_b32_e32 v159, 4, v183
	v_xor_b32_e32 v159, v159, v180
	v_lshlrev_b32_e32 v159, 4, v159
	v_lshl_add_u32 v159, v182, 7, v159
	v_or_b32_e32 v160, 6, v183
	v_xor_b32_e32 v160, v160, v180
	v_lshlrev_b32_e32 v160, 4, v160
	v_lshl_add_u32 v160, v182, 7, v160
	v_bfe_u32 v182, v181, 2, 2
	v_lshl_add_u32 v180, v183, 2, v182
	v_lshlrev_b32_e32 v180, 8, v180
	v_bfe_u32 v183, v181, 4, 1
	v_lshlrev_b32_e32 v183, 5, v183
	v_add_u32_e32 v180, v180, v183
	v_bfe_u32 v183, v181, 1, 1
	v_lshlrev_b32_e32 v183, 4, v183
	v_add_u32_e32 v180, v180, v183
	v_and_b32_e32 v183, 1, v181
	v_lshl_add_u32 v180, v183, 3, v180
	v_xor_b32_e32 v161, 0, v182
	v_lshl_add_u32 v161, v161, 6, v180
	v_xor_b32_e32 v162, 1, v182
	v_lshl_add_u32 v162, v162, 6, v180
	v_xor_b32_e32 v163, 2, v182
	v_lshl_add_u32 v163, v163, 6, v180
	v_xor_b32_e32 v164, 3, v182
	v_lshl_add_u32 v164, v164, 6, v180
	s_mov_b32 s7, 0
.Lat_stream:
	s_lshl_b32 s8, s7, 7
	s_mov_b32 s9, 0
	v_lshl_add_u64 v[182:183], v[166:167], 0, s[8:9]
	global_load_dwordx4 v[150:153], v[182:183], off
	global_load_dwordx4 v[146:149], v[182:183], off offset:32
	global_load_dwordx4 v[142:145], v[182:183], off offset:64
	global_load_dwordx4 v[138:141], v[182:183], off offset:96
	s_lshl_b64 s[14:15], s[46:47], 12
	s_add_u32 s14, s14, s74
	s_addc_u32 s15, s15, s75
	s_add_u32 s18, s14, 0x800
	s_addc_u32 s19, s15, 0
	s_add_i32 s8, s8, 0x400
	s_add_u32 s14, s14, s8
	s_addc_u32 s15, s15, 0
	s_mov_b32 s13, 0
	s_mov_b32 s17, 32768
	s_mov_b32 s85, 0
	s_add_i32 m0, s13, s68
	s_nop 0
	global_load_lds_dwordx4 v154, s[14:15]
	s_add_i32 m0, s17, s69
	s_nop 0
	global_load_lds_dwordx4 v155, s[18:19]
	s_add_i32 m0, m0, 0x400
	s_nop 0
	global_load_lds_dwordx4 v156, s[18:19]
	s_add_i32 s13, s13, 8192
	s_cmp_eq_u32 s13, 32768
	s_cselect_b32 s13, 0, s13
	s_add_i32 s17, s17, 16384
	s_cmp_eq_u32 s17, 114688
	s_cselect_b32 s17, 32768, s17
	s_add_i32 s85, s85, 1
	s_cmp_lt_u32 s85, s6
	s_cselect_b32 s8, 0x40000, 0
	s_add_u32 s14, s14, s8
	s_addc_u32 s15, s15, 0
	s_add_u32 s18, s18, s8
	s_addc_u32 s19, s19, 0
	s_add_i32 m0, s13, s68
	s_nop 0
	global_load_lds_dwordx4 v154, s[14:15]
	s_add_i32 m0, s17, s69
	s_nop 0
	global_load_lds_dwordx4 v155, s[18:19]
	s_add_i32 m0, m0, 0x400
	s_nop 0
	global_load_lds_dwordx4 v156, s[18:19]
	s_add_i32 s13, s13, 8192
	s_cmp_eq_u32 s13, 32768
	s_cselect_b32 s13, 0, s13
	s_add_i32 s17, s17, 16384
	s_cmp_eq_u32 s17, 114688
	s_cselect_b32 s17, 32768, s17
	s_add_i32 s85, s85, 1
	s_cmp_lt_u32 s85, s6
	s_cselect_b32 s8, 0x40000, 0
	s_add_u32 s14, s14, s8
	s_addc_u32 s15, s15, 0
	s_add_u32 s18, s18, s8
	s_addc_u32 s19, s19, 0
	s_add_i32 m0, s13, s68
	s_nop 0
	global_load_lds_dwordx4 v154, s[14:15]
	s_add_i32 m0, s17, s69
	s_nop 0
	global_load_lds_dwordx4 v155, s[18:19]
	s_add_i32 m0, m0, 0x400
	s_nop 0
	global_load_lds_dwordx4 v156, s[18:19]
	s_add_i32 s13, s13, 8192
	s_cmp_eq_u32 s13, 32768
	s_cselect_b32 s13, 0, s13
	s_add_i32 s17, s17, 16384
	s_cmp_eq_u32 s17, 114688
	s_cselect_b32 s17, 32768, s17
	s_add_i32 s85, s85, 1
	s_cmp_lt_u32 s85, s6
	s_cselect_b32 s8, 0x40000, 0
	s_add_u32 s14, s14, s8
	s_addc_u32 s15, s15, 0
	s_add_u32 s18, s18, s8
	s_addc_u32 s19, s19, 0
	v_mov_b32_e32 v0, 0
	v_mov_b32_e32 v1, v0
	v_mov_b32_e32 v2, v0
	v_mov_b32_e32 v3, v0
	v_mov_b32_e32 v4, v0
	v_mov_b32_e32 v5, v0
	v_mov_b32_e32 v6, v0
	v_mov_b32_e32 v7, v0
	v_mov_b32_e32 v8, v0
	v_mov_b32_e32 v9, v0
	v_mov_b32_e32 v10, v0
	v_mov_b32_e32 v11, v0
	v_mov_b32_e32 v12, v0
	v_mov_b32_e32 v13, v0
	v_mov_b32_e32 v14, v0
	v_mov_b32_e32 v15, v0
	v_mov_b32_e32 v16, v0
	v_mov_b32_e32 v17, v0
	v_mov_b32_e32 v18, v0
	v_mov_b32_e32 v19, v0
	v_mov_b32_e32 v20, v0
	v_mov_b32_e32 v21, v0
	v_mov_b32_e32 v22, v0
	v_mov_b32_e32 v23, v0
	v_mov_b32_e32 v24, v0
	v_mov_b32_e32 v25, v0
	v_mov_b32_e32 v26, v0
	v_mov_b32_e32 v27, v0
	v_mov_b32_e32 v28, v0
	v_mov_b32_e32 v29, v0
	v_mov_b32_e32 v30, v0
	v_mov_b32_e32 v31, v0
	v_mov_b32_e32 v32, v0
	v_mov_b32_e32 v33, v0
	v_mov_b32_e32 v34, v0
	v_mov_b32_e32 v35, v0
	v_mov_b32_e32 v36, v0
	v_mov_b32_e32 v37, v0
	v_mov_b32_e32 v38, v0
	v_mov_b32_e32 v39, v0
	v_mov_b32_e32 v40, v0
	v_mov_b32_e32 v41, v0
	v_mov_b32_e32 v42, v0
	v_mov_b32_e32 v43, v0
	v_mov_b32_e32 v44, v0
	v_mov_b32_e32 v45, v0
	v_mov_b32_e32 v46, v0
	v_mov_b32_e32 v47, v0
	v_mov_b32_e32 v48, v0
	v_mov_b32_e32 v49, v0
	v_mov_b32_e32 v50, v0
	v_mov_b32_e32 v51, v0
	v_mov_b32_e32 v52, v0
	v_mov_b32_e32 v53, v0
	v_mov_b32_e32 v54, v0
	v_mov_b32_e32 v55, v0
	v_mov_b32_e32 v56, v0
	v_mov_b32_e32 v57, v0
	v_mov_b32_e32 v58, v0
	v_mov_b32_e32 v59, v0
	v_mov_b32_e32 v60, v0
	v_mov_b32_e32 v61, v0
	v_mov_b32_e32 v62, v0
	v_mov_b32_e32 v63, v0
	v_mov_b32_e32 v64, v0
	v_mov_b32_e32 v65, v0
	v_mov_b32_e32 v66, v0
	v_mov_b32_e32 v67, v0
	v_mov_b32_e32 v68, v0
	v_mov_b32_e32 v69, v0
	v_mov_b32_e32 v70, v0
	v_mov_b32_e32 v71, v0
	v_mov_b32_e32 v72, v0
	v_mov_b32_e32 v73, v0
	v_mov_b32_e32 v74, v0
	v_mov_b32_e32 v75, v0
	v_mov_b32_e32 v76, v0
	v_mov_b32_e32 v77, v0
	v_mov_b32_e32 v78, v0
	v_mov_b32_e32 v79, v0
	v_mov_b32_e32 v80, 0
	v_mov_b32_e32 v81, 0
	s_mov_b32 s5, 0
	s_waitcnt vmcnt(3)
	s_barrier
	s_add_i32 m0, s13, s68
	s_nop 0
	global_load_lds_dwordx4 v154, s[14:15]
	s_add_i32 m0, s17, s69
	s_nop 0
	global_load_lds_dwordx4 v155, s[18:19]
	s_add_i32 m0, m0, 0x400
	s_nop 0
	global_load_lds_dwordx4 v156, s[18:19]
	s_add_i32 s13, s13, 8192
	s_cmp_eq_u32 s13, 32768
	s_cselect_b32 s13, 0, s13
	s_add_i32 s17, s17, 16384
	s_cmp_eq_u32 s17, 114688
	s_cselect_b32 s17, 32768, s17
	s_add_i32 s85, s85, 1
	s_cmp_lt_u32 s85, s6
	s_cselect_b32 s8, 0x40000, 0
	s_add_u32 s14, s14, s8
	s_addc_u32 s15, s15, 0
	s_add_u32 s18, s18, s8
	s_addc_u32 s19, s19, 0
	s_mov_b32 s12, 0
	v_add_u32_e32 v188, s12, v157
	v_add_u32_e32 v189, s12, v158
	v_add_u32_e32 v222, s12, v159
	v_add_u32_e32 v223, s12, v160
	ds_read_b128 v[224:227], v188
	ds_read_b128 v[228:231], v188 offset:4096
	ds_read_b128 v[232:235], v189
	ds_read_b128 v[236:239], v189 offset:4096
	ds_read_b128 v[240:243], v222
	ds_read_b128 v[130:133], v222 offset:4096
	ds_read_b128 v[134:137], v223
	ds_read_b128 v[184:187], v223 offset:4096
	s_waitcnt lgkmcnt(7)
	v_mfma_f32_32x32x16_bf16 v[82:97], v[224:227], v[150:153], v[64:79]
	s_waitcnt lgkmcnt(6)
	v_mfma_f32_32x32x16_bf16 v[98:113], v[228:231], v[150:153], v[64:79]
	s_waitcnt lgkmcnt(5)
	v_mfma_f32_32x32x16_bf16 v[82:97], v[232:235], v[146:149], v[82:97]
	s_waitcnt lgkmcnt(4)
	v_mfma_f32_32x32x16_bf16 v[98:113], v[236:239], v[146:149], v[98:113]
	s_waitcnt lgkmcnt(3)
	v_mfma_f32_32x32x16_bf16 v[82:97], v[240:243], v[142:145], v[82:97]
	s_waitcnt lgkmcnt(2)
	v_mfma_f32_32x32x16_bf16 v[98:113], v[130:133], v[142:145], v[98:113]
	s_waitcnt lgkmcnt(1)
	v_mfma_f32_32x32x16_bf16 v[82:97], v[134:137], v[138:141], v[82:97]
	s_waitcnt lgkmcnt(0)
	v_mfma_f32_32x32x16_bf16 v[98:113], v[184:187], v[138:141], v[98:113]
	s_nop 11
	v_max_f32_e32 v181, v82, v98
	v_max3_f32 v181, v181, v83, v99
	v_max3_f32 v181, v181, v84, v100
	v_max3_f32 v181, v181, v85, v101
	v_max3_f32 v181, v181, v86, v102
	v_max3_f32 v181, v181, v87, v103
	v_max3_f32 v181, v181, v88, v104
	v_max3_f32 v181, v181, v89, v105
	v_max3_f32 v181, v181, v90, v106
	v_max3_f32 v181, v181, v91, v107
	v_max3_f32 v181, v181, v92, v108
	v_max3_f32 v181, v181, v93, v109
	v_max3_f32 v181, v181, v94, v110
	v_max3_f32 v181, v181, v95, v111
	v_max3_f32 v181, v181, v96, v112
	v_max3_f32 v181, v181, v97, v113
	ds_bpermute_b32 v182, v214, v181
	s_waitcnt lgkmcnt(0)
	v_max_f32_e32 v80, v181, v182
	v_xor_b32_e32 v64, 0x80000000, v80
	v_mov_b32_e32 v65, v64
	v_mov_b32_e32 v66, v64
	v_mov_b32_e32 v67, v64
	v_mov_b32_e32 v68, v64
	v_mov_b32_e32 v69, v64
	v_mov_b32_e32 v70, v64
	v_mov_b32_e32 v71, v64
	v_mov_b32_e32 v72, v64
	v_mov_b32_e32 v73, v64
	v_mov_b32_e32 v74, v64
	v_mov_b32_e32 v75, v64
	v_mov_b32_e32 v76, v64
	v_mov_b32_e32 v77, v64
	v_mov_b32_e32 v78, v64
	v_mov_b32_e32 v79, v64
	v_sub_f32_e32 v82, v82, v80
	v_sub_f32_e32 v83, v83, v80
	v_sub_f32_e32 v84, v84, v80
	v_sub_f32_e32 v85, v85, v80
	v_sub_f32_e32 v86, v86, v80
	v_sub_f32_e32 v87, v87, v80
	v_sub_f32_e32 v88, v88, v80
	v_sub_f32_e32 v89, v89, v80
	v_sub_f32_e32 v90, v90, v80
	v_sub_f32_e32 v91, v91, v80
	v_sub_f32_e32 v92, v92, v80
	v_sub_f32_e32 v93, v93, v80
	v_sub_f32_e32 v94, v94, v80
	v_sub_f32_e32 v95, v95, v80
	v_sub_f32_e32 v96, v96, v80
	v_sub_f32_e32 v97, v97, v80
	v_sub_f32_e32 v98, v98, v80
	v_sub_f32_e32 v99, v99, v80
	v_sub_f32_e32 v100, v100, v80
	v_sub_f32_e32 v101, v101, v80
	v_sub_f32_e32 v102, v102, v80
	v_sub_f32_e32 v103, v103, v80
	v_sub_f32_e32 v104, v104, v80
	v_sub_f32_e32 v105, v105, v80
	v_sub_f32_e32 v106, v106, v80
	v_sub_f32_e32 v107, v107, v80
	v_sub_f32_e32 v108, v108, v80
	v_sub_f32_e32 v109, v109, v80
	v_sub_f32_e32 v110, v110, v80
	v_sub_f32_e32 v111, v111, v80
	v_sub_f32_e32 v112, v112, v80
	v_sub_f32_e32 v113, v113, v80
	v_mov_b32_e32 v180, 0
	v_exp_f32_e32 v82, v82
	v_exp_f32_e32 v83, v83
	v_add_f32_e32 v180, v180, v82
	v_exp_f32_e32 v84, v84
	v_add_f32_e32 v180, v180, v83
	v_exp_f32_e32 v85, v85
	v_add_f32_e32 v180, v180, v84
	v_exp_f32_e32 v86, v86
	v_add_f32_e32 v180, v180, v85
	v_exp_f32_e32 v87, v87
	v_add_f32_e32 v180, v180, v86
	v_exp_f32_e32 v88, v88
	v_add_f32_e32 v180, v180, v87
	v_exp_f32_e32 v89, v89
	v_add_f32_e32 v180, v180, v88
	v_exp_f32_e32 v90, v90
	v_add_f32_e32 v180, v180, v89
	v_exp_f32_e32 v91, v91
	v_add_f32_e32 v180, v180, v90
	v_exp_f32_e32 v92, v92
	v_add_f32_e32 v180, v180, v91
	v_exp_f32_e32 v93, v93
	v_add_f32_e32 v180, v180, v92
	v_exp_f32_e32 v94, v94
	v_add_f32_e32 v180, v180, v93
	v_exp_f32_e32 v95, v95
	v_add_f32_e32 v180, v180, v94
	v_exp_f32_e32 v96, v96
	v_add_f32_e32 v180, v180, v95
	v_exp_f32_e32 v97, v97
	v_add_f32_e32 v180, v180, v96
	v_exp_f32_e32 v98, v98
	v_add_f32_e32 v180, v180, v97
	v_exp_f32_e32 v99, v99
	v_add_f32_e32 v180, v180, v98
	v_exp_f32_e32 v100, v100
	v_add_f32_e32 v180, v180, v99
	v_exp_f32_e32 v101, v101
	v_add_f32_e32 v180, v180, v100
	v_exp_f32_e32 v102, v102
	v_add_f32_e32 v180, v180, v101
	v_exp_f32_e32 v103, v103
	v_add_f32_e32 v180, v180, v102
	v_exp_f32_e32 v104, v104
	v_add_f32_e32 v180, v180, v103
	v_exp_f32_e32 v105, v105
	v_add_f32_e32 v180, v180, v104
	v_exp_f32_e32 v106, v106
	v_add_f32_e32 v180, v180, v105
	v_exp_f32_e32 v107, v107
	v_add_f32_e32 v180, v180, v106
	v_exp_f32_e32 v108, v108
	v_add_f32_e32 v180, v180, v107
	v_exp_f32_e32 v109, v109
	v_add_f32_e32 v180, v180, v108
	v_exp_f32_e32 v110, v110
	v_add_f32_e32 v180, v180, v109
	v_exp_f32_e32 v111, v111
	v_add_f32_e32 v180, v180, v110
	v_exp_f32_e32 v112, v112
	v_add_f32_e32 v180, v180, v111
	v_exp_f32_e32 v113, v113
	v_add_f32_e32 v180, v180, v112
	s_nop 0
	v_add_f32_e32 v180, v180, v113
	v_cvt_pk_bf16_f32 v114, v82, v83
	v_cvt_pk_bf16_f32 v115, v84, v85
	v_cvt_pk_bf16_f32 v116, v86, v87
	v_cvt_pk_bf16_f32 v117, v88, v89
	v_cvt_pk_bf16_f32 v118, v90, v91
	v_cvt_pk_bf16_f32 v119, v92, v93
	v_cvt_pk_bf16_f32 v120, v94, v95
	v_cvt_pk_bf16_f32 v121, v96, v97
	v_cvt_pk_bf16_f32 v122, v98, v99
	v_cvt_pk_bf16_f32 v123, v100, v101
	v_cvt_pk_bf16_f32 v124, v102, v103
	v_cvt_pk_bf16_f32 v125, v104, v105
	v_cvt_pk_bf16_f32 v126, v106, v107
	v_cvt_pk_bf16_f32 v127, v108, v109
	v_cvt_pk_bf16_f32 v128, v110, v111
	v_cvt_pk_bf16_f32 v129, v112, v113
	v_cmp_ngt_f32_e32 vcc, s23, v180
	s_cbranch_vccz .Lat_norescale_1
	ds_bpermute_b32 v182, v214, v180
	s_waitcnt lgkmcnt(0)
	v_add_f32_e32 v182, v180, v182
	v_min_f32_e32 v182, 0x7f61b1e6, v182
	v_log_f32_e32 v182, v182
	s_nop 0
	v_floor_f32_e32 v182, v182
	v_max_f32_e32 v182, 0, v182
	v_exp_f32_e64 v183, -v182
	v_add_f32_e32 v80, v80, v182
	v_mul_f32_e32 v81, v81, v183
	v_mul_f32_e32 v180, v180, v183
	v_xor_b32_e32 v64, 0x80000000, v80
	v_mov_b32_e32 v65, v64
	v_mov_b32_e32 v66, v64
	v_mov_b32_e32 v67, v64
	v_mov_b32_e32 v68, v64
	v_mov_b32_e32 v69, v64
	v_mov_b32_e32 v70, v64
	v_mov_b32_e32 v71, v64
	v_mov_b32_e32 v72, v64
	v_mov_b32_e32 v73, v64
	v_mov_b32_e32 v74, v64
	v_mov_b32_e32 v75, v64
	v_mov_b32_e32 v76, v64
	v_mov_b32_e32 v77, v64
	v_mov_b32_e32 v78, v64
	v_mov_b32_e32 v79, v64
	v_mul_f32_e32 v82, v82, v183
	v_mul_f32_e32 v83, v83, v183
	v_mul_f32_e32 v84, v84, v183
	v_mul_f32_e32 v85, v85, v183
	v_mul_f32_e32 v86, v86, v183
	v_mul_f32_e32 v87, v87, v183
	v_mul_f32_e32 v88, v88, v183
	v_mul_f32_e32 v89, v89, v183
	v_mul_f32_e32 v90, v90, v183
	v_mul_f32_e32 v91, v91, v183
	v_mul_f32_e32 v92, v92, v183
	v_mul_f32_e32 v93, v93, v183
	v_mul_f32_e32 v94, v94, v183
	v_mul_f32_e32 v95, v95, v183
	v_mul_f32_e32 v96, v96, v183
	v_mul_f32_e32 v97, v97, v183
	v_mul_f32_e32 v98, v98, v183
	v_mul_f32_e32 v99, v99, v183
	v_mul_f32_e32 v100, v100, v183
	v_mul_f32_e32 v101, v101, v183
	v_mul_f32_e32 v102, v102, v183
	v_mul_f32_e32 v103, v103, v183
	v_mul_f32_e32 v104, v104, v183
	v_mul_f32_e32 v105, v105, v183
	v_mul_f32_e32 v106, v106, v183
	v_mul_f32_e32 v107, v107, v183
	v_mul_f32_e32 v108, v108, v183
	v_mul_f32_e32 v109, v109, v183
	v_mul_f32_e32 v110, v110, v183
	v_mul_f32_e32 v111, v111, v183
	v_mul_f32_e32 v112, v112, v183
	v_mul_f32_e32 v113, v113, v183
	v_mul_f32_e32 v0, v0, v183
	v_mul_f32_e32 v1, v1, v183
	v_mul_f32_e32 v2, v2, v183
	v_mul_f32_e32 v3, v3, v183
	v_mul_f32_e32 v4, v4, v183
	v_mul_f32_e32 v5, v5, v183
	v_mul_f32_e32 v6, v6, v183
	v_mul_f32_e32 v7, v7, v183
	v_mul_f32_e32 v8, v8, v183
	v_mul_f32_e32 v9, v9, v183
	v_mul_f32_e32 v10, v10, v183
	v_mul_f32_e32 v11, v11, v183
	v_mul_f32_e32 v12, v12, v183
	v_mul_f32_e32 v13, v13, v183
	v_mul_f32_e32 v14, v14, v183
	v_mul_f32_e32 v15, v15, v183
	v_mul_f32_e32 v16, v16, v183
	v_mul_f32_e32 v17, v17, v183
	v_mul_f32_e32 v18, v18, v183
	v_mul_f32_e32 v19, v19, v183
	v_mul_f32_e32 v20, v20, v183
	v_mul_f32_e32 v21, v21, v183
	v_mul_f32_e32 v22, v22, v183
	v_mul_f32_e32 v23, v23, v183
	v_mul_f32_e32 v24, v24, v183
	v_mul_f32_e32 v25, v25, v183
	v_mul_f32_e32 v26, v26, v183
	v_mul_f32_e32 v27, v27, v183
	v_mul_f32_e32 v28, v28, v183
	v_mul_f32_e32 v29, v29, v183
	v_mul_f32_e32 v30, v30, v183
	v_mul_f32_e32 v31, v31, v183
	v_mul_f32_e32 v32, v32, v183
	v_mul_f32_e32 v33, v33, v183
	v_mul_f32_e32 v34, v34, v183
	v_mul_f32_e32 v35, v35, v183
	v_mul_f32_e32 v36, v36, v183
	v_mul_f32_e32 v37, v37, v183
	v_mul_f32_e32 v38, v38, v183
	v_mul_f32_e32 v39, v39, v183
	v_mul_f32_e32 v40, v40, v183
	v_mul_f32_e32 v41, v41, v183
	v_mul_f32_e32 v42, v42, v183
	v_mul_f32_e32 v43, v43, v183
	v_mul_f32_e32 v44, v44, v183
	v_mul_f32_e32 v45, v45, v183
	v_mul_f32_e32 v46, v46, v183
	v_mul_f32_e32 v47, v47, v183
	v_mul_f32_e32 v48, v48, v183
	v_mul_f32_e32 v49, v49, v183
	v_mul_f32_e32 v50, v50, v183
	v_mul_f32_e32 v51, v51, v183
	v_mul_f32_e32 v52, v52, v183
	v_mul_f32_e32 v53, v53, v183
	v_mul_f32_e32 v54, v54, v183
	v_mul_f32_e32 v55, v55, v183
	v_mul_f32_e32 v56, v56, v183
	v_mul_f32_e32 v57, v57, v183
	v_mul_f32_e32 v58, v58, v183
	v_mul_f32_e32 v59, v59, v183
	v_mul_f32_e32 v60, v60, v183
	v_mul_f32_e32 v61, v61, v183
	v_mul_f32_e32 v62, v62, v183
	v_mul_f32_e32 v63, v63, v183
	v_cvt_pk_bf16_f32 v114, v82, v83
	v_cvt_pk_bf16_f32 v115, v84, v85
	v_cvt_pk_bf16_f32 v116, v86, v87
	v_cvt_pk_bf16_f32 v117, v88, v89
	v_cvt_pk_bf16_f32 v118, v90, v91
	v_cvt_pk_bf16_f32 v119, v92, v93
	v_cvt_pk_bf16_f32 v120, v94, v95
	v_cvt_pk_bf16_f32 v121, v96, v97
	v_cvt_pk_bf16_f32 v122, v98, v99
	v_cvt_pk_bf16_f32 v123, v100, v101
	v_cvt_pk_bf16_f32 v124, v102, v103
	v_cvt_pk_bf16_f32 v125, v104, v105
	v_cvt_pk_bf16_f32 v126, v106, v107
	v_cvt_pk_bf16_f32 v127, v108, v109
	v_cvt_pk_bf16_f32 v128, v110, v111
	v_cvt_pk_bf16_f32 v129, v112, v113
.Lat_norescale_1:
	v_add_f32_e32 v81, v81, v180
	s_cmp_lt_i32 s81, 1
	s_cbranch_scc1 .Lat_noqk1_2
	s_mov_b32 s12, 8192
	v_add_u32_e32 v188, s12, v157
	v_add_u32_e32 v189, s12, v158
	v_add_u32_e32 v222, s12, v159
	v_add_u32_e32 v223, s12, v160
	ds_read_b128 v[224:227], v188
	ds_read_b128 v[228:231], v188 offset:4096
	ds_read_b128 v[232:235], v189
	ds_read_b128 v[236:239], v189 offset:4096
	ds_read_b128 v[240:243], v222
	ds_read_b128 v[130:133], v222 offset:4096
	ds_read_b128 v[134:137], v223
	ds_read_b128 v[184:187], v223 offset:4096
	s_waitcnt lgkmcnt(7)
	v_mfma_f32_32x32x16_bf16 v[82:97], v[224:227], v[150:153], v[64:79]
	s_waitcnt lgkmcnt(6)
	v_mfma_f32_32x32x16_bf16 v[98:113], v[228:231], v[150:153], v[64:79]
	s_waitcnt lgkmcnt(5)
	v_mfma_f32_32x32x16_bf16 v[82:97], v[232:235], v[146:149], v[82:97]
	s_waitcnt lgkmcnt(4)
	v_mfma_f32_32x32x16_bf16 v[98:113], v[236:239], v[146:149], v[98:113]
	s_waitcnt lgkmcnt(3)
	v_mfma_f32_32x32x16_bf16 v[82:97], v[240:243], v[142:145], v[82:97]
	s_waitcnt lgkmcnt(2)
	v_mfma_f32_32x32x16_bf16 v[98:113], v[130:133], v[142:145], v[98:113]
	s_waitcnt lgkmcnt(1)
	v_mfma_f32_32x32x16_bf16 v[82:97], v[134:137], v[138:141], v[82:97]
	s_waitcnt lgkmcnt(0)
	v_mfma_f32_32x32x16_bf16 v[98:113], v[184:187], v[138:141], v[98:113]
.Lat_noqk1_2:
	s_mov_b32 s5, 1
	s_mov_b32 s12, 16384
	s_mov_b32 s84, 32768
	v_add_u32_e32 v215, s84, v161
	v_add_u32_e32 v165, s84, v162
	v_add_u32_e32 v216, s84, v163
	v_add_u32_e32 v217, s84, v164
	ds_read_b64_tr_b16 v[224:225], v215 offset:0
	ds_read_b64_tr_b16 v[226:227], v215 offset:2048
	ds_read_b64_tr_b16 v[228:229], v165 offset:0
	ds_read_b64_tr_b16 v[230:231], v165 offset:2048
	ds_read_b64_tr_b16 v[232:233], v216 offset:0
	ds_read_b64_tr_b16 v[234:235], v216 offset:2048
	ds_read_b64_tr_b16 v[236:237], v217 offset:0
	ds_read_b64_tr_b16 v[238:239], v217 offset:2048
	s_waitcnt vmcnt(3) lgkmcnt(8)
	s_barrier
.Lat_loop:
	s_add_i32 m0, s13, s68
	s_nop 0
	global_load_lds_dwordx4 v154, s[14:15]
	s_add_i32 m0, s17, s69
	s_nop 0
	global_load_lds_dwordx4 v155, s[18:19]
	s_add_i32 m0, m0, 0x400
	s_nop 0
	global_load_lds_dwordx4 v156, s[18:19]
	s_add_i32 s13, s13, 8192
	s_cmp_eq_u32 s13, 32768
	s_cselect_b32 s13, 0, s13
	s_add_i32 s17, s17, 16384
	s_cmp_eq_u32 s17, 114688
	s_cselect_b32 s17, 32768, s17
	s_add_i32 s85, s85, 1
	s_cmp_lt_u32 s85, s6
	s_cselect_b32 s8, 0x40000, 0
	s_add_u32 s14, s14, s8
	s_addc_u32 s15, s15, 0
	s_add_u32 s18, s18, s8
	s_addc_u32 s19, s19, 0
	s_add_i32 s16, s81, 1
	s_cmp_gt_i32 s5, s16
	s_cbranch_scc1 .Lat_xdone_3
	v_add_u32_e32 v188, s12, v157
	v_add_u32_e32 v189, s12, v158
	v_add_u32_e32 v222, s12, v159
	v_add_u32_e32 v223, s12, v160
	s_cmp_gt_i32 s5, s81
	s_cbranch_scc1 .Lat_pvonly_4
	ds_read_b64_tr_b16 v[240:241], v215 offset:4096
	ds_read_b64_tr_b16 v[242:243], v215 offset:6144
	ds_read_b64_tr_b16 v[130:131], v165 offset:4096
	ds_read_b64_tr_b16 v[132:133], v165 offset:6144
	ds_read_b64_tr_b16 v[134:135], v216 offset:4096
	ds_read_b64_tr_b16 v[136:137], v216 offset:6144
	ds_read_b64_tr_b16 v[184:185], v217 offset:4096
	ds_read_b64_tr_b16 v[186:187], v217 offset:6144
	s_waitcnt lgkmcnt(14)
	v_mfma_f32_32x32x16_bf16 v[0:15], v[224:227], v[114:117], v[0:15]
	v_exp_f32_e32 v82, v82
	v_exp_f32_e32 v83, v83
	v_mov_b32_e32 v180, 0
	s_waitcnt lgkmcnt(12)
	v_mfma_f32_32x32x16_bf16 v[16:31], v[228:231], v[114:117], v[16:31]
	v_exp_f32_e32 v84, v84
	v_exp_f32_e32 v85, v85
	v_add_f32_e32 v180, v180, v82
	v_add_f32_e32 v180, v180, v83
	s_waitcnt lgkmcnt(10)
	v_mfma_f32_32x32x16_bf16 v[32:47], v[232:235], v[114:117], v[32:47]
	v_exp_f32_e32 v86, v86
	v_exp_f32_e32 v87, v87
	v_add_f32_e32 v180, v180, v84
	v_add_f32_e32 v180, v180, v85
	s_waitcnt lgkmcnt(8)
	v_mfma_f32_32x32x16_bf16 v[48:63], v[236:239], v[114:117], v[48:63]
	v_exp_f32_e32 v88, v88
	v_exp_f32_e32 v89, v89
	v_add_f32_e32 v180, v180, v86
	v_add_f32_e32 v180, v180, v87
	ds_read_b64_tr_b16 v[224:225], v215 offset:8192
	ds_read_b64_tr_b16 v[226:227], v215 offset:10240
	ds_read_b64_tr_b16 v[228:229], v165 offset:8192
	ds_read_b64_tr_b16 v[230:231], v165 offset:10240
	ds_read_b64_tr_b16 v[232:233], v216 offset:8192
	ds_read_b64_tr_b16 v[234:235], v216 offset:10240
	ds_read_b64_tr_b16 v[236:237], v217 offset:8192
	ds_read_b64_tr_b16 v[238:239], v217 offset:10240
	s_waitcnt lgkmcnt(14)
	v_mfma_f32_32x32x16_bf16 v[0:15], v[240:243], v[118:121], v[0:15]
	v_exp_f32_e32 v90, v90
	v_exp_f32_e32 v91, v91
	v_add_f32_e32 v180, v180, v88
	v_add_f32_e32 v180, v180, v89
	v_cvt_pk_bf16_f32 v114, v82, v83
	s_waitcnt lgkmcnt(12)
	v_mfma_f32_32x32x16_bf16 v[16:31], v[130:133], v[118:121], v[16:31]
	v_exp_f32_e32 v92, v92
	v_exp_f32_e32 v93, v93
	v_add_f32_e32 v180, v180, v90
	v_add_f32_e32 v180, v180, v91
	v_cvt_pk_bf16_f32 v115, v84, v85
	s_waitcnt lgkmcnt(10)
	v_mfma_f32_32x32x16_bf16 v[32:47], v[134:137], v[118:121], v[32:47]
	v_exp_f32_e32 v94, v94
	v_exp_f32_e32 v95, v95
	v_add_f32_e32 v180, v180, v92
	v_add_f32_e32 v180, v180, v93
	v_cvt_pk_bf16_f32 v116, v86, v87
	s_waitcnt lgkmcnt(8)
	v_mfma_f32_32x32x16_bf16 v[48:63], v[184:187], v[118:121], v[48:63]
	v_exp_f32_e32 v96, v96
	v_exp_f32_e32 v97, v97
	v_add_f32_e32 v180, v180, v94
	v_add_f32_e32 v180, v180, v95
	v_cvt_pk_bf16_f32 v117, v88, v89
	ds_read_b64_tr_b16 v[240:241], v215 offset:12288
	ds_read_b64_tr_b16 v[242:243], v215 offset:14336
	ds_read_b64_tr_b16 v[130:131], v165 offset:12288
	ds_read_b64_tr_b16 v[132:133], v165 offset:14336
	ds_read_b64_tr_b16 v[134:135], v216 offset:12288
	ds_read_b64_tr_b16 v[136:137], v216 offset:14336
	ds_read_b64_tr_b16 v[184:185], v217 offset:12288
	ds_read_b64_tr_b16 v[186:187], v217 offset:14336
	s_waitcnt lgkmcnt(14)
	v_mfma_f32_32x32x16_bf16 v[0:15], v[224:227], v[122:125], v[0:15]
	v_exp_f32_e32 v98, v98
	v_exp_f32_e32 v99, v99
	v_add_f32_e32 v180, v180, v96
	v_add_f32_e32 v180, v180, v97
	v_cvt_pk_bf16_f32 v118, v90, v91
	s_waitcnt lgkmcnt(12)
	v_mfma_f32_32x32x16_bf16 v[16:31], v[228:231], v[122:125], v[16:31]
	v_exp_f32_e32 v100, v100
	v_exp_f32_e32 v101, v101
	v_add_f32_e32 v180, v180, v98
	v_add_f32_e32 v180, v180, v99
	v_cvt_pk_bf16_f32 v119, v92, v93
	s_waitcnt lgkmcnt(10)
	v_mfma_f32_32x32x16_bf16 v[32:47], v[232:235], v[122:125], v[32:47]
	v_exp_f32_e32 v102, v102
	v_exp_f32_e32 v103, v103
	v_add_f32_e32 v180, v180, v100
	v_add_f32_e32 v180, v180, v101
	v_cvt_pk_bf16_f32 v120, v94, v95
	s_waitcnt lgkmcnt(8)
	v_mfma_f32_32x32x16_bf16 v[48:63], v[236:239], v[122:125], v[48:63]
	v_exp_f32_e32 v104, v104
	v_exp_f32_e32 v105, v105
	v_add_f32_e32 v180, v180, v102
	v_add_f32_e32 v180, v180, v103
	v_cvt_pk_bf16_f32 v121, v96, v97
	ds_read_b128 v[224:227], v188
	ds_read_b128 v[228:231], v188 offset:4096
	ds_read_b128 v[232:235], v189
	ds_read_b128 v[236:239], v189 offset:4096
	s_waitcnt lgkmcnt(10)
	v_mfma_f32_32x32x16_bf16 v[0:15], v[240:243], v[126:129], v[0:15]
	v_exp_f32_e32 v106, v106
	v_exp_f32_e32 v107, v107
	v_add_f32_e32 v180, v180, v104
	v_add_f32_e32 v180, v180, v105
	v_cvt_pk_bf16_f32 v122, v98, v99
	s_waitcnt lgkmcnt(8)
	v_mfma_f32_32x32x16_bf16 v[16:31], v[130:133], v[126:129], v[16:31]
	v_exp_f32_e32 v108, v108
	v_exp_f32_e32 v109, v109
	v_add_f32_e32 v180, v180, v106
	v_add_f32_e32 v180, v180, v107
	v_cvt_pk_bf16_f32 v123, v100, v101
	s_waitcnt lgkmcnt(6)
	v_mfma_f32_32x32x16_bf16 v[32:47], v[134:137], v[126:129], v[32:47]
	v_exp_f32_e32 v110, v110
	v_exp_f32_e32 v111, v111
	v_add_f32_e32 v180, v180, v108
	v_add_f32_e32 v180, v180, v109
	v_cvt_pk_bf16_f32 v124, v102, v103
	s_waitcnt lgkmcnt(4)
	v_mfma_f32_32x32x16_bf16 v[48:63], v[184:187], v[126:129], v[48:63]
	v_exp_f32_e32 v112, v112
	v_exp_f32_e32 v113, v113
	v_add_f32_e32 v180, v180, v110
	v_add_f32_e32 v180, v180, v111
	v_cvt_pk_bf16_f32 v125, v104, v105
	s_nop 0
	v_add_f32_e32 v180, v180, v112
	v_add_f32_e32 v180, v180, v113
	v_cvt_pk_bf16_f32 v126, v106, v107
	v_cvt_pk_bf16_f32 v127, v108, v109
	v_cvt_pk_bf16_f32 v128, v110, v111
	v_cvt_pk_bf16_f32 v129, v112, v113
	v_cmp_ngt_f32_e32 vcc, s23, v180
	s_cbranch_vccz .Lat_norescale_5
	ds_bpermute_b32 v182, v214, v180
	s_waitcnt lgkmcnt(0)
	v_add_f32_e32 v182, v180, v182
	v_min_f32_e32 v182, 0x7f61b1e6, v182
	v_log_f32_e32 v182, v182
	s_nop 0
	v_floor_f32_e32 v182, v182
	v_max_f32_e32 v182, 0, v182
	v_exp_f32_e64 v183, -v182
	v_add_f32_e32 v80, v80, v182
	v_mul_f32_e32 v81, v81, v183
	v_mul_f32_e32 v180, v180, v183
	v_xor_b32_e32 v64, 0x80000000, v80
	v_mov_b32_e32 v65, v64
	v_mov_b32_e32 v66, v64
	v_mov_b32_e32 v67, v64
	v_mov_b32_e32 v68, v64
	v_mov_b32_e32 v69, v64
	v_mov_b32_e32 v70, v64
	v_mov_b32_e32 v71, v64
	v_mov_b32_e32 v72, v64
	v_mov_b32_e32 v73, v64
	v_mov_b32_e32 v74, v64
	v_mov_b32_e32 v75, v64
	v_mov_b32_e32 v76, v64
	v_mov_b32_e32 v77, v64
	v_mov_b32_e32 v78, v64
	v_mov_b32_e32 v79, v64
	v_mul_f32_e32 v82, v82, v183
	v_mul_f32_e32 v83, v83, v183
	v_mul_f32_e32 v84, v84, v183
	v_mul_f32_e32 v85, v85, v183
	v_mul_f32_e32 v86, v86, v183
	v_mul_f32_e32 v87, v87, v183
	v_mul_f32_e32 v88, v88, v183
	v_mul_f32_e32 v89, v89, v183
	v_mul_f32_e32 v90, v90, v183
	v_mul_f32_e32 v91, v91, v183
	v_mul_f32_e32 v92, v92, v183
	v_mul_f32_e32 v93, v93, v183
	v_mul_f32_e32 v94, v94, v183
	v_mul_f32_e32 v95, v95, v183
	v_mul_f32_e32 v96, v96, v183
	v_mul_f32_e32 v97, v97, v183
	v_mul_f32_e32 v98, v98, v183
	v_mul_f32_e32 v99, v99, v183
	v_mul_f32_e32 v100, v100, v183
	v_mul_f32_e32 v101, v101, v183
	v_mul_f32_e32 v102, v102, v183
	v_mul_f32_e32 v103, v103, v183
	v_mul_f32_e32 v104, v104, v183
	v_mul_f32_e32 v105, v105, v183
	v_mul_f32_e32 v106, v106, v183
	v_mul_f32_e32 v107, v107, v183
	v_mul_f32_e32 v108, v108, v183
	v_mul_f32_e32 v109, v109, v183
	v_mul_f32_e32 v110, v110, v183
	v_mul_f32_e32 v111, v111, v183
	v_mul_f32_e32 v112, v112, v183
	v_mul_f32_e32 v113, v113, v183
	v_mul_f32_e32 v0, v0, v183
	v_mul_f32_e32 v1, v1, v183
	v_mul_f32_e32 v2, v2, v183
	v_mul_f32_e32 v3, v3, v183
	v_mul_f32_e32 v4, v4, v183
	v_mul_f32_e32 v5, v5, v183
	v_mul_f32_e32 v6, v6, v183
	v_mul_f32_e32 v7, v7, v183
	v_mul_f32_e32 v8, v8, v183
	v_mul_f32_e32 v9, v9, v183
	v_mul_f32_e32 v10, v10, v183
	v_mul_f32_e32 v11, v11, v183
	v_mul_f32_e32 v12, v12, v183
	v_mul_f32_e32 v13, v13, v183
	v_mul_f32_e32 v14, v14, v183
	v_mul_f32_e32 v15, v15, v183
	v_mul_f32_e32 v16, v16, v183
	v_mul_f32_e32 v17, v17, v183
	v_mul_f32_e32 v18, v18, v183
	v_mul_f32_e32 v19, v19, v183
	v_mul_f32_e32 v20, v20, v183
	v_mul_f32_e32 v21, v21, v183
	v_mul_f32_e32 v22, v22, v183
	v_mul_f32_e32 v23, v23, v183
	v_mul_f32_e32 v24, v24, v183
	v_mul_f32_e32 v25, v25, v183
	v_mul_f32_e32 v26, v26, v183
	v_mul_f32_e32 v27, v27, v183
	v_mul_f32_e32 v28, v28, v183
	v_mul_f32_e32 v29, v29, v183
	v_mul_f32_e32 v30, v30, v183
	v_mul_f32_e32 v31, v31, v183
	v_mul_f32_e32 v32, v32, v183
	v_mul_f32_e32 v33, v33, v183
	v_mul_f32_e32 v34, v34, v183
	v_mul_f32_e32 v35, v35, v183
	v_mul_f32_e32 v36, v36, v183
	v_mul_f32_e32 v37, v37, v183
	v_mul_f32_e32 v38, v38, v183
	v_mul_f32_e32 v39, v39, v183
	v_mul_f32_e32 v40, v40, v183
	v_mul_f32_e32 v41, v41, v183
	v_mul_f32_e32 v42, v42, v183
	v_mul_f32_e32 v43, v43, v183
	v_mul_f32_e32 v44, v44, v183
	v_mul_f32_e32 v45, v45, v183
	v_mul_f32_e32 v46, v46, v183
	v_mul_f32_e32 v47, v47, v183
	v_mul_f32_e32 v48, v48, v183
	v_mul_f32_e32 v49, v49, v183
	v_mul_f32_e32 v50, v50, v183
	v_mul_f32_e32 v51, v51, v183
	v_mul_f32_e32 v52, v52, v183
	v_mul_f32_e32 v53, v53, v183
	v_mul_f32_e32 v54, v54, v183
	v_mul_f32_e32 v55, v55, v183
	v_mul_f32_e32 v56, v56, v183
	v_mul_f32_e32 v57, v57, v183
	v_mul_f32_e32 v58, v58, v183
	v_mul_f32_e32 v59, v59, v183
	v_mul_f32_e32 v60, v60, v183
	v_mul_f32_e32 v61, v61, v183
	v_mul_f32_e32 v62, v62, v183
	v_mul_f32_e32 v63, v63, v183
	v_cvt_pk_bf16_f32 v114, v82, v83
	v_cvt_pk_bf16_f32 v115, v84, v85
	v_cvt_pk_bf16_f32 v116, v86, v87
	v_cvt_pk_bf16_f32 v117, v88, v89
	v_cvt_pk_bf16_f32 v118, v90, v91
	v_cvt_pk_bf16_f32 v119, v92, v93
	v_cvt_pk_bf16_f32 v120, v94, v95
	v_cvt_pk_bf16_f32 v121, v96, v97
	v_cvt_pk_bf16_f32 v122, v98, v99
	v_cvt_pk_bf16_f32 v123, v100, v101
	v_cvt_pk_bf16_f32 v124, v102, v103
	v_cvt_pk_bf16_f32 v125, v104, v105
	v_cvt_pk_bf16_f32 v126, v106, v107
	v_cvt_pk_bf16_f32 v127, v108, v109
	v_cvt_pk_bf16_f32 v128, v110, v111
	v_cvt_pk_bf16_f32 v129, v112, v113

.Lat_pvonly_4:
	ds_read_b64_tr_b16 v[240:241], v215 offset:4096
	ds_read_b64_tr_b16 v[242:243], v215 offset:6144
	ds_read_b64_tr_b16 v[130:131], v165 offset:4096
	ds_read_b64_tr_b16 v[132:133], v165 offset:6144
	ds_read_b64_tr_b16 v[134:135], v216 offset:4096
	ds_read_b64_tr_b16 v[136:137], v216 offset:6144
	ds_read_b64_tr_b16 v[184:185], v217 offset:4096
	ds_read_b64_tr_b16 v[186:187], v217 offset:6144
	s_waitcnt lgkmcnt(14)
	v_mfma_f32_32x32x16_bf16 v[0:15], v[224:227], v[114:117], v[0:15]
	s_waitcnt lgkmcnt(12)
	v_mfma_f32_32x32x16_bf16 v[16:31], v[228:231], v[114:117], v[16:31]
	s_waitcnt lgkmcnt(10)
	v_mfma_f32_32x32x16_bf16 v[32:47], v[232:235], v[114:117], v[32:47]
	s_waitcnt lgkmcnt(8)
	v_mfma_f32_32x32x16_bf16 v[48:63], v[236:239], v[114:117], v[48:63]
	ds_read_b64_tr_b16 v[224:225], v215 offset:8192
	ds_read_b64_tr_b16 v[226:227], v215 offset:10240
	ds_read_b64_tr_b16 v[228:229], v165 offset:8192
	ds_read_b64_tr_b16 v[230:231], v165 offset:10240
	ds_read_b64_tr_b16 v[232:233], v216 offset:8192
	ds_read_b64_tr_b16 v[234:235], v216 offset:10240
	ds_read_b64_tr_b16 v[236:237], v217 offset:8192
	ds_read_b64_tr_b16 v[238:239], v217 offset:10240
	s_waitcnt lgkmcnt(14)
	v_mfma_f32_32x32x16_bf16 v[0:15], v[240:243], v[118:121], v[0:15]
	s_waitcnt lgkmcnt(12)
	v_mfma_f32_32x32x16_bf16 v[16:31], v[130:133], v[118:121], v[16:31]
	s_waitcnt lgkmcnt(10)
	v_mfma_f32_32x32x16_bf16 v[32:47], v[134:137], v[118:121], v[32:47]
	s_waitcnt lgkmcnt(8)
	v_mfma_f32_32x32x16_bf16 v[48:63], v[184:187], v[118:121], v[48:63]
	ds_read_b64_tr_b16 v[240:241], v215 offset:12288
	ds_read_b64_tr_b16 v[242:243], v215 offset:14336
	ds_read_b64_tr_b16 v[130:131], v165 offset:12288
	ds_read_b64_tr_b16 v[132:133], v165 offset:14336
	ds_read_b64_tr_b16 v[134:135], v216 offset:12288
	ds_read_b64_tr_b16 v[136:137], v216 offset:14336
	ds_read_b64_tr_b16 v[184:185], v217 offset:12288
	ds_read_b64_tr_b16 v[186:187], v217 offset:14336
	s_waitcnt lgkmcnt(14)
	v_mfma_f32_32x32x16_bf16 v[0:15], v[224:227], v[122:125], v[0:15]
	s_waitcnt lgkmcnt(12)
	v_mfma_f32_32x32x16_bf16 v[16:31], v[228:231], v[122:125], v[16:31]
	s_waitcnt lgkmcnt(10)
	v_mfma_f32_32x32x16_bf16 v[32:47], v[232:235], v[122:125], v[32:47]
	s_waitcnt lgkmcnt(8)
	v_mfma_f32_32x32x16_bf16 v[48:63], v[236:239], v[122:125], v[48:63]
	s_waitcnt lgkmcnt(6)
	v_mfma_f32_32x32x16_bf16 v[0:15], v[240:243], v[126:129], v[0:15]
	s_waitcnt lgkmcnt(4)
	v_mfma_f32_32x32x16_bf16 v[16:31], v[130:133], v[126:129], v[16:31]
	s_waitcnt lgkmcnt(2)
	v_mfma_f32_32x32x16_bf16 v[32:47], v[134:137], v[126:129], v[32:47]
	s_waitcnt lgkmcnt(0)
	v_mfma_f32_32x32x16_bf16 v[48:63], v[184:187], v[126:129], v[48:63]
.Lat_xdone_3:
	s_add_i32 s8, s5, 1
	s_cmp_gt_i32 s8, s81
	s_cbranch_scc1 .Lat_noqk_6
	ds_read_b128 v[240:243], v222
	ds_read_b128 v[130:133], v222 offset:4096
	ds_read_b128 v[134:137], v223
	ds_read_b128 v[184:187], v223 offset:4096
	s_waitcnt lgkmcnt(7)
	v_mfma_f32_32x32x16_bf16 v[82:97], v[224:227], v[150:153], v[64:79]
	s_waitcnt lgkmcnt(6)
	v_mfma_f32_32x32x16_bf16 v[98:113], v[228:231], v[150:153], v[64:79]
	s_waitcnt lgkmcnt(5)
	v_mfma_f32_32x32x16_bf16 v[82:97], v[232:235], v[146:149], v[82:97]
	s_waitcnt lgkmcnt(4)
	v_mfma_f32_32x32x16_bf16 v[98:113], v[236:239], v[146:149], v[98:113]
	s_waitcnt lgkmcnt(3)
	v_mfma_f32_32x32x16_bf16 v[82:97], v[240:243], v[142:145], v[82:97]
	s_waitcnt lgkmcnt(2)
	v_mfma_f32_32x32x16_bf16 v[98:113], v[130:133], v[142:145], v[98:113]
	s_waitcnt lgkmcnt(1)
	v_mfma_f32_32x32x16_bf16 v[82:97], v[134:137], v[138:141], v[82:97]
	s_waitcnt lgkmcnt(0)
	v_mfma_f32_32x32x16_bf16 v[98:113], v[184:187], v[138:141], v[98:113]
.Lat_noqk_6:
	s_add_i32 s5, s5, 1
	s_add_i32 s12, s12, 8192
	s_cmp_eq_u32 s12, 32768
	s_cselect_b32 s12, 0, s12
	s_add_i32 s84, s84, 16384
	s_cmp_eq_u32 s84, 114688
	s_cselect_b32 s84, 32768, s84
	s_add_i32 s16, s81, 1
	s_cmp_gt_i32 s5, s16
	s_cbranch_scc1 .Lat_novpre_7
	v_add_u32_e32 v215, s84, v161
	v_add_u32_e32 v165, s84, v162
	v_add_u32_e32 v216, s84, v163
	v_add_u32_e32 v217, s84, v164
	ds_read_b64_tr_b16 v[224:225], v215 offset:0
	ds_read_b64_tr_b16 v[226:227], v215 offset:2048
	ds_read_b64_tr_b16 v[228:229], v165 offset:0
	ds_read_b64_tr_b16 v[230:231], v165 offset:2048
	ds_read_b64_tr_b16 v[232:233], v216 offset:0
	ds_read_b64_tr_b16 v[234:235], v216 offset:2048
	ds_read_b64_tr_b16 v[236:237], v217 offset:0
	ds_read_b64_tr_b16 v[238:239], v217 offset:2048
	s_waitcnt vmcnt(3) lgkmcnt(8)
	s_barrier
	s_branch .Lat_joined_8
.Lat_novpre_7:
	s_waitcnt vmcnt(3) lgkmcnt(0)
	s_barrier
.Lat_joined_8:
	s_cmp_lt_u32 s5, s6
	s_cbranch_scc1 .Lat_loop
	s_add_i32 s16, s81, 1
	s_cmp_gt_i32 s5, s16
	s_cbranch_scc1 .Lat_nolast_9
	ds_read_b64_tr_b16 v[240:241], v215 offset:4096
	ds_read_b64_tr_b16 v[242:243], v215 offset:6144
	ds_read_b64_tr_b16 v[130:131], v165 offset:4096
	ds_read_b64_tr_b16 v[132:133], v165 offset:6144
	ds_read_b64_tr_b16 v[134:135], v216 offset:4096
	ds_read_b64_tr_b16 v[136:137], v216 offset:6144
	ds_read_b64_tr_b16 v[184:185], v217 offset:4096
	ds_read_b64_tr_b16 v[186:187], v217 offset:6144
	s_waitcnt lgkmcnt(14)
	v_mfma_f32_32x32x16_bf16 v[0:15], v[224:227], v[114:117], v[0:15]
	s_waitcnt lgkmcnt(12)
	v_mfma_f32_32x32x16_bf16 v[16:31], v[228:231], v[114:117], v[16:31]
	s_waitcnt lgkmcnt(10)
	v_mfma_f32_32x32x16_bf16 v[32:47], v[232:235], v[114:117], v[32:47]
	s_waitcnt lgkmcnt(8)
	v_mfma_f32_32x32x16_bf16 v[48:63], v[236:239], v[114:117], v[48:63]
	ds_read_b64_tr_b16 v[224:225], v215 offset:8192
	ds_read_b64_tr_b16 v[226:227], v215 offset:10240
	ds_read_b64_tr_b16 v[228:229], v165 offset:8192
	ds_read_b64_tr_b16 v[230:231], v165 offset:10240
	ds_read_b64_tr_b16 v[232:233], v216 offset:8192
	ds_read_b64_tr_b16 v[234:235], v216 offset:10240
	ds_read_b64_tr_b16 v[236:237], v217 offset:8192
	ds_read_b64_tr_b16 v[238:239], v217 offset:10240
	s_waitcnt lgkmcnt(14)
	v_mfma_f32_32x32x16_bf16 v[0:15], v[240:243], v[118:121], v[0:15]
	s_waitcnt lgkmcnt(12)
	v_mfma_f32_32x32x16_bf16 v[16:31], v[130:133], v[118:121], v[16:31]
	s_waitcnt lgkmcnt(10)
	v_mfma_f32_32x32x16_bf16 v[32:47], v[134:137], v[118:121], v[32:47]
	s_waitcnt lgkmcnt(8)
	v_mfma_f32_32x32x16_bf16 v[48:63], v[184:187], v[118:121], v[48:63]
	ds_read_b64_tr_b16 v[240:241], v215 offset:12288
	ds_read_b64_tr_b16 v[242:243], v215 offset:14336
	ds_read_b64_tr_b16 v[130:131], v165 offset:12288
	ds_read_b64_tr_b16 v[132:133], v165 offset:14336
	ds_read_b64_tr_b16 v[134:135], v216 offset:12288
	ds_read_b64_tr_b16 v[136:137], v216 offset:14336
	ds_read_b64_tr_b16 v[184:185], v217 offset:12288
	ds_read_b64_tr_b16 v[186:187], v217 offset:14336
	s_waitcnt lgkmcnt(14)
	v_mfma_f32_32x32x16_bf16 v[0:15], v[224:227], v[122:125], v[0:15]
	s_waitcnt lgkmcnt(12)
	v_mfma_f32_32x32x16_bf16 v[16:31], v[228:231], v[122:125], v[16:31]
	s_waitcnt lgkmcnt(10)
	v_mfma_f32_32x32x16_bf16 v[32:47], v[232:235], v[122:125], v[32:47]
	s_waitcnt lgkmcnt(8)
	v_mfma_f32_32x32x16_bf16 v[48:63], v[236:239], v[122:125], v[48:63]
	s_waitcnt lgkmcnt(6)
	v_mfma_f32_32x32x16_bf16 v[0:15], v[240:243], v[126:129], v[0:15]
	s_waitcnt lgkmcnt(4)
	v_mfma_f32_32x32x16_bf16 v[16:31], v[130:133], v[126:129], v[16:31]
	s_waitcnt lgkmcnt(2)
	v_mfma_f32_32x32x16_bf16 v[32:47], v[134:137], v[126:129], v[32:47]
	s_waitcnt lgkmcnt(0)
	v_mfma_f32_32x32x16_bf16 v[48:63], v[184:187], v[126:129], v[48:63]
.Lat_nolast_9:
	s_waitcnt vmcnt(0) lgkmcnt(0)
	s_barrier
	ds_bpermute_b32 v182, v214, v81
	s_waitcnt lgkmcnt(0)
	v_add_f32_e32 v64, v81, v182
	v_div_scale_f32 v65, s[36:37], v64, v64, 1.0
	v_rcp_f32_e32 v66, v65
	v_div_scale_f32 v67, vcc, 1.0, v64, 1.0
	v_fma_f32 v68, -v65, v66, 1.0
	v_fmac_f32_e32 v66, v68, v66
	v_mul_f32_e32 v68, v67, v66
	v_fma_f32 v69, -v65, v68, v67
	v_fmac_f32_e32 v68, v69, v66
	v_fma_f32 v65, -v65, v68, v67
	v_div_fmas_f32 v65, v65, v66, v68
	v_div_fixup_f32 v72, v65, v64, 1.0
	v_mul_f32_e32 v0, v0, v72
	v_mul_f32_e32 v1, v1, v72
	v_mul_f32_e32 v2, v2, v72
	v_mul_f32_e32 v3, v3, v72
	v_mul_f32_e32 v4, v4, v72
	v_mul_f32_e32 v5, v5, v72
	v_mul_f32_e32 v6, v6, v72
	v_mul_f32_e32 v7, v7, v72
	v_mul_f32_e32 v8, v8, v72
	v_mul_f32_e32 v9, v9, v72
	v_mul_f32_e32 v10, v10, v72
	v_mul_f32_e32 v11, v11, v72
	v_mul_f32_e32 v12, v12, v72
	v_mul_f32_e32 v13, v13, v72
	v_mul_f32_e32 v14, v14, v72
	v_mul_f32_e32 v15, v15, v72
	v_mul_f32_e32 v16, v16, v72
	v_mul_f32_e32 v17, v17, v72
	v_mul_f32_e32 v18, v18, v72
	v_mul_f32_e32 v19, v19, v72
	v_mul_f32_e32 v20, v20, v72
	v_mul_f32_e32 v21, v21, v72
	v_mul_f32_e32 v22, v22, v72
	v_mul_f32_e32 v23, v23, v72
	v_mul_f32_e32 v24, v24, v72
	v_mul_f32_e32 v25, v25, v72
	v_mul_f32_e32 v26, v26, v72
	v_mul_f32_e32 v27, v27, v72
	v_mul_f32_e32 v28, v28, v72
	v_mul_f32_e32 v29, v29, v72
	v_mul_f32_e32 v30, v30, v72
	v_mul_f32_e32 v31, v31, v72
	v_mul_f32_e32 v32, v32, v72
	v_mul_f32_e32 v33, v33, v72
	v_mul_f32_e32 v34, v34, v72
	v_mul_f32_e32 v35, v35, v72
	v_mul_f32_e32 v36, v36, v72
	v_mul_f32_e32 v37, v37, v72
	v_mul_f32_e32 v38, v38, v72
	v_mul_f32_e32 v39, v39, v72
	v_mul_f32_e32 v40, v40, v72
	v_mul_f32_e32 v41, v41, v72
	v_mul_f32_e32 v42, v42, v72
	v_mul_f32_e32 v43, v43, v72
	v_mul_f32_e32 v44, v44, v72
	v_mul_f32_e32 v45, v45, v72
	v_mul_f32_e32 v46, v46, v72
	v_mul_f32_e32 v47, v47, v72
	v_mul_f32_e32 v48, v48, v72
	v_mul_f32_e32 v49, v49, v72
	v_mul_f32_e32 v50, v50, v72
	v_mul_f32_e32 v51, v51, v72
	v_mul_f32_e32 v52, v52, v72
	v_mul_f32_e32 v53, v53, v72
	v_mul_f32_e32 v54, v54, v72
	v_mul_f32_e32 v55, v55, v72
	v_mul_f32_e32 v56, v56, v72
	v_mul_f32_e32 v57, v57, v72
	v_mul_f32_e32 v58, v58, v72
	v_mul_f32_e32 v59, v59, v72
	v_mul_f32_e32 v60, v60, v72
	v_mul_f32_e32 v61, v61, v72
	v_mul_f32_e32 v62, v62, v72
	v_mul_f32_e32 v63, v63, v72
	s_cmp_lg_u32 s7, 0
	s_cbranch_scc1 .Lat_combine
	global_store_dwordx4 v[170:171], v[0:3], off
	global_store_dwordx4 v[170:171], v[4:7], off offset:16
	global_store_dwordx4 v[170:171], v[8:11], off offset:32
	global_store_dwordx4 v[170:171], v[12:15], off offset:48
	global_store_dwordx4 v[170:171], v[16:19], off offset:64
	global_store_dwordx4 v[170:171], v[20:23], off offset:80
	global_store_dwordx4 v[170:171], v[24:27], off offset:96
	global_store_dwordx4 v[170:171], v[28:31], off offset:112
	global_store_dwordx4 v[170:171], v[32:35], off offset:128
	global_store_dwordx4 v[170:171], v[36:39], off offset:144
	global_store_dwordx4 v[170:171], v[40:43], off offset:160
	global_store_dwordx4 v[170:171], v[44:47], off offset:176
	global_store_dwordx4 v[170:171], v[48:51], off offset:192
	global_store_dwordx4 v[170:171], v[52:55], off offset:208
	global_store_dwordx4 v[170:171], v[56:59], off offset:224
	global_store_dwordx4 v[170:171], v[60:63], off offset:240
	s_mov_b32 s7, 1
	s_branch .Lat_stream
